# G3 epilogue: rstd masked once per row group and (v_mul, v_cndmask) pairs fused into v_mul_legacy_f32; asm-marker hazard pads dropped
# speedup vs baseline: 1.0108x; 1.0108x over previous
; __device__ __forceinline__ float bperm_f(int src_lane, float v) { return __builtin_bit_cast(float, __builtin_amdgcn_ds_bpermute(src_lane << 2, __builtin_bit_cast(int, v))); }
;     __device__ __forceinline__ void operator()(Acc& acc, const Unit& u, int wr, int wc, int fr, int fq) const {
;         const int b = u.pm / UPU, j = u.pm % UPU;
;         const int tbase = 252 * j + 126 * wr - 2 + fr;
;         const int ch0 = 128 * u.pn + 32 * wc + 8 * fq;
;         float chain = 0.f;
;         { const int ln = (fq << 4) | fr; f32x4 pq[8];
; #pragma unroll
;           for (int q = 0; q < 8; ++q) { const int t = tbase + 16 * q; const bool ok = (t >= 0) && (t < SEQ); pq[q] = *(const f32x4*)(ssq + (size_t)(b * SEQ + (ok ? t : 0)) * 16 + 4 * fq); }
; #pragma unroll
;           for (int q = 0; q < 8; ++q) {
;             const int t = tbase + 16 * q; const bool ok = (t >= 0) && (t < SEQ);
;             float sq = (pq[q][0] + pq[q][1]) + (pq[q][2] + pq[q][3]); sq += bperm_f(ln ^ 16, sq); sq += bperm_f(ln ^ 32, sq);
;             const float rs = rsqrtf(sq * (1.0f / DM) + EPS);
; #pragma unroll
;             for (int bj = 0; bj < 2; ++bj)
; #pragma unroll
;                 for (int n = 0; n < 2; ++n)
; #pragma unroll
;                     for (int i = 0; i < 4; ++i) { const float v = acc[q >> 2][bj][q & 3][n][i]; acc[q >> 2][bj][q & 3][n][i] = ok ? v * rs : 0.f; }
;           }
.LBB0_43:
	s_mul_hi_i32 s21, s20, 0x3e0f83e1
	s_lshr_b32 s27, s21, 31
	s_ashr_i32 s21, s21, 3
	s_add_i32 s21, s21, s27
	s_mul_i32 s27, s21, 33
	s_sub_i32 s20, s20, s27
	s_mulk_i32 s20, 0xfc
	v_add_u32_e32 v198, s20, v194
	v_add_u32_e32 v223, 16, v198
	v_cmp_gt_u32_e64 s[56:57], s97, v198
	v_cmp_gt_u32_e64 s[52:53], s97, v223
	s_lshl_b32 s20, s21, 13
	v_cndmask_b32_e64 v132, 0, v198, s[56:57]
	v_cndmask_b32_e64 v136, 0, v223, s[52:53]
	v_add_u32_e32 v132, s20, v132
	v_add_u32_e32 v136, s20, v136
	v_ashrrev_i32_e32 v133, 31, v132
	v_ashrrev_i32_e32 v137, 31, v136
	v_lshlrev_b64 v[132:133], 6, v[132:133]
	v_lshlrev_b64 v[136:137], 6, v[136:137]
	v_lshl_add_u64 v[132:133], v[146:147], 0, v[132:133]
	v_lshl_add_u64 v[136:137], v[146:147], 0, v[136:137]
	flat_load_dwordx4 v[132:135], v[132:133]
	v_add_u32_e32 v227, 32, v198
	flat_load_dwordx4 v[136:139], v[136:137]
	v_add_u32_e32 v226, 48, v198
	v_cmp_gt_u32_e64 s[54:55], s97, v227
	v_add_u32_e32 v225, 64, v198
	v_cmp_gt_u32_e64 s[50:51], s97, v226
	v_cndmask_b32_e64 v152, 0, v227, s[54:55]
	v_cmp_gt_u32_e64 s[48:49], s97, v225
	v_cndmask_b32_e64 v153, 0, v226, s[50:51]
	v_add_u32_e32 v152, s20, v152
	v_cndmask_b32_e64 v155, 0, v225, s[48:49]
	v_add_u32_e32 v154, s20, v153
	v_ashrrev_i32_e32 v153, 31, v152
	v_add_u32_e32 v156, s20, v155
	v_ashrrev_i32_e32 v155, 31, v154
	v_lshlrev_b64 v[152:153], 6, v[152:153]
	v_lshlrev_b64 v[154:155], 6, v[154:155]
	v_add_u32_e32 v224, 0x50, v198
	v_cmp_gt_u32_e64 s[46:47], s97, v224
	s_mov_b32 s44, 0x358637bd
	v_add_u32_e32 v222, 0x60, v198
	v_add_u32_e32 v199, 0x70, v198
	v_cndmask_b32_e64 v157, 0, v224, s[46:47]
	v_mov_b64_e32 v[188:189], s[44:45]
	v_cmp_gt_u32_e64 s[44:45], s97, v222
	v_cmp_gt_u32_e32 vcc, s97, v199
	v_add_u32_e32 v158, s20, v157
	v_ashrrev_i32_e32 v157, 31, v156
	v_cndmask_b32_e64 v159, 0, v222, s[44:45]
	v_cndmask_b32_e32 v161, 0, v199, vcc
	v_lshlrev_b64 v[156:157], 6, v[156:157]
	s_mov_b32 s90, 0x3a800000
	v_add_u32_e32 v160, s20, v159
	v_add_u32_e32 v162, s20, v161
	v_ashrrev_i32_e32 v159, 31, v158
	v_ashrrev_i32_e32 v161, 31, v160
	v_ashrrev_i32_e32 v163, 31, v162
	v_lshlrev_b64 v[158:159], 6, v[158:159]
	v_lshlrev_b64 v[160:161], 6, v[160:161]
	v_lshlrev_b64 v[162:163], 6, v[162:163]
	s_waitcnt vmcnt(0) lgkmcnt(0)
	v_mov_b32_e32 v174, v133
	v_mov_b32_e32 v175, v134
	v_mov_b32_e32 v133, v135
	v_mov_b32_e32 v134, v137
	v_mov_b32_e32 v135, v138
	v_mov_b32_e32 v137, v139
	v_pk_add_f32 v[132:133], v[174:175], v[132:133]
	v_pk_add_f32 v[134:135], v[134:135], v[136:137]
	v_mov_b32_e32 v137, v132
	v_mov_b32_e32 v136, v134
	v_mov_b32_e32 v132, v135
	v_pk_add_f32 v[132:133], v[136:137], v[132:133]
	v_lshl_add_u64 v[136:137], v[146:147], 0, v[152:153]
	v_lshl_add_u64 v[138:139], v[146:147], 0, v[154:155]
	flat_load_dwordx4 v[190:193], v[136:137]
	flat_load_dwordx4 v[228:231], v[138:139]
	ds_bpermute_b32 v135, v195, v133
	ds_bpermute_b32 v134, v195, v132
	v_lshl_add_u64 v[136:137], v[146:147], 0, v[156:157]
	v_lshl_add_u64 v[138:139], v[146:147], 0, v[158:159]
	v_lshl_add_u64 v[152:153], v[146:147], 0, v[160:161]
	v_lshl_add_u64 v[154:155], v[146:147], 0, v[162:163]
	s_waitcnt lgkmcnt(0)
	v_pk_add_f32 v[132:133], v[132:133], v[134:135]
	ds_bpermute_b32 v135, v196, v133
	ds_bpermute_b32 v134, v196, v132
	s_waitcnt lgkmcnt(0)
	v_pk_add_f32 v[132:133], v[132:133], v[134:135]
	s_nop 0
	v_pk_fma_f32 v[156:157], v[132:133], s[90:91], v[188:189] op_sel_hi:[1,0,0]
	s_nop 0
	v_mul_f32_e32 v132, 0x4b800000, v157
	v_cmp_gt_f32_e64 s[58:59], s29, v157
	s_nop 1
	v_cndmask_b32_e64 v132, v157, v132, s[58:59]
	v_rsq_f32_e32 v157, v132
	flat_load_dwordx4 v[232:235], v[136:137]
	flat_load_dwordx4 v[236:239], v[138:139]
	s_nop 0
	flat_load_dwordx4 v[136:139], v[152:153]
	flat_load_dwordx4 v[132:135], v[154:155]
	v_mul_f32_e32 v152, 0x45800000, v157
	v_cndmask_b32_e64 v153, v157, v152, s[58:59]
	v_mul_f32_e32 v157, v122, v153
	v_cndmask_b32_e64 v153, 0, v153, s[56:57]
	v_mul_legacy_f32 v122, v126, v153
	v_mul_legacy_f32 v152, v108, v153
	v_mul_f32_e32 v108, v109, v153
	v_mul_f32_e32 v109, 0x4b800000, v156
	v_cmp_gt_f32_e64 s[58:59], s29, v156
	v_cndmask_b32_e64 v109, v156, v109, s[58:59]
	v_rsq_f32_e32 v109, v109
	v_mul_legacy_f32 v182, v128, v153
	v_cndmask_b32_e64 v128, 0, v108, s[56:57]
	v_mul_legacy_f32 v160, v130, v153
	v_mul_legacy_f32 v130, v124, v153
	v_mul_legacy_f32 v124, v110, v153
	v_mul_legacy_f32 v110, v111, v153
	v_mul_f32_e32 v108, 0x45800000, v109
	v_cndmask_b32_e64 v108, v109, v108, s[58:59]
	v_cndmask_b32_e64 v108, 0, v108, s[52:53]
	v_mul_legacy_f32 v187, v116, v108
	v_mul_legacy_f32 v181, v117, v108
	v_mul_legacy_f32 v175, v118, v108
	v_cndmask_b32_e64 v162, 0, v157, s[56:57]
	v_mul_legacy_f32 v157, v119, v108
	v_mul_legacy_f32 v119, v112, v108
	v_mul_legacy_f32 v117, v113, v108
	v_mul_legacy_f32 v186, v104, v108
	v_mul_legacy_f32 v113, v114, v108
	v_mul_f32_e32 v109, v115, v108
	v_mul_legacy_f32 v180, v105, v108
	v_mul_legacy_f32 v174, v106, v108
	v_mul_legacy_f32 v156, v107, v108
	v_mul_legacy_f32 v118, v92, v108
	s_waitcnt vmcnt(0)
	v_mov_b32_e32 v104, v191
	v_mov_b32_e32 v105, v192
	v_mov_b32_e32 v191, v193
	v_mov_b32_e32 v114, v229
	v_mov_b32_e32 v115, v230
	v_mov_b32_e32 v229, v231
	v_pk_add_f32 v[104:105], v[104:105], v[190:191]
	v_pk_add_f32 v[114:115], v[114:115], v[228:229]
	v_mov_b32_e32 v191, v104
	v_mov_b32_e32 v190, v114
	v_mov_b32_e32 v104, v115
	v_pk_add_f32 v[104:105], v[190:191], v[104:105]
	ds_bpermute_b32 v115, v195, v105
	ds_bpermute_b32 v114, v195, v104
	v_mul_legacy_f32 v116, v93, v108
	s_waitcnt lgkmcnt(0)
	v_pk_add_f32 v[104:105], v[104:105], v[114:115]
	ds_bpermute_b32 v107, v196, v105
	ds_bpermute_b32 v106, v196, v104
	v_mul_f32_e32 v155, v120, v153
	v_mul_legacy_f32 v178, v121, v153
	s_waitcnt lgkmcnt(0)
; __device__ __forceinline__ float bperm_f(int src_lane, float v) { return __builtin_bit_cast(float, __builtin_amdgcn_ds_bpermute(src_lane << 2, __builtin_bit_cast(int, v))); }
;     __device__ __forceinline__ void operator()(Acc& acc, const Unit& u, int wr, int wc, int fr, int fq) const {
;     ...
;           for (int q = 0; q < 8; ++q) {
;             const int t = tbase + 16 * q; const bool ok = (t >= 0) && (t < SEQ);
;             float sq = (pq[q][0] + pq[q][1]) + (pq[q][2] + pq[q][3]); sq += bperm_f(ln ^ 16, sq); sq += bperm_f(ln ^ 32, sq);
;             const float rs = rsqrtf(sq * (1.0f / DM) + EPS);
; #pragma unroll
;             for (int bj = 0; bj < 2; ++bj)
; #pragma unroll
;                 for (int n = 0; n < 2; ++n)
; #pragma unroll
;                     for (int i = 0; i < 4; ++i) { const float v = acc[q >> 2][bj][q & 3][n][i]; acc[q >> 2][bj][q & 3][n][i] = ok ? v * rs : 0.f; }
;           }
	v_pk_add_f32 v[92:93], v[104:105], v[106:107]
	v_mul_legacy_f32 v176, v129, v153
	v_pk_fma_f32 v[92:93], v[92:93], s[90:91], v[188:189] op_sel_hi:[1,0,0]
	v_mul_legacy_f32 v154, v131, v153
	v_mul_legacy_f32 v126, v125, v153
	v_mul_legacy_f32 v120, v127, v153
	v_cndmask_b32_e64 v184, 0, v155, s[56:57]
	v_mul_legacy_f32 v158, v123, v153
	v_mul_f32_e32 v104, 0x4b800000, v93
	v_cmp_gt_f32_e64 s[56:57], s29, v93
	v_mul_legacy_f32 v112, v94, v108
	v_cndmask_b32_e64 v93, v93, v104, s[56:57]
	v_rsq_f32_e32 v93, v93
	v_mul_legacy_f32 v108, v95, v108
	v_cndmask_b32_e64 v109, 0, v109, s[52:53]
	v_mul_f32_e32 v94, 0x45800000, v93
	v_cndmask_b32_e64 v111, v93, v94, s[56:57]
	v_mul_f32_e32 v93, v100, v111
	v_cndmask_b32_e64 v111, 0, v111, s[54:55]
	v_mul_legacy_f32 v100, v76, v111
	v_mul_f32_e32 v76, v77, v111
	v_mul_f32_e32 v77, 0x4b800000, v92
	v_cmp_gt_f32_e64 s[52:53], s29, v92
	v_cndmask_b32_e64 v115, 0, v93, s[54:55]
	v_cndmask_b32_e64 v77, v92, v77, s[52:53]
	v_mul_legacy_f32 v107, v101, v111
	v_rsq_f32_e32 v77, v77
	v_mul_legacy_f32 v105, v102, v111
	v_mul_legacy_f32 v103, v103, v111
	v_mul_f32_e32 v93, v96, v111
	v_cndmask_b32_e64 v96, 0, v76, s[54:55]
	v_mul_legacy_f32 v94, v78, v111
	v_mul_legacy_f32 v92, v79, v111
	v_mul_f32_e32 v76, 0x45800000, v77
	v_cndmask_b32_e64 v101, 0, v93, s[54:55]
	v_cndmask_b32_e64 v76, v77, v76, s[52:53]
	v_mul_legacy_f32 v97, v97, v111
	v_mul_legacy_f32 v114, v88, v111
	v_mul_legacy_f32 v95, v98, v111
	v_mul_f32_e32 v93, v99, v111
	v_mul_legacy_f32 v106, v89, v111
	v_cndmask_b32_e64 v76, 0, v76, s[50:51]
	v_mul_legacy_f32 v99, v84, v76
	v_mul_legacy_f32 v104, v90, v111
	v_mul_f32_e32 v88, v91, v111
	v_mul_legacy_f32 v91, v85, v76
	v_mul_legacy_f32 v89, v86, v76
	v_mul_legacy_f32 v87, v87, v76
	v_mul_legacy_f32 v85, v80, v76
	v_mul_legacy_f32 v81, v81, v76
	v_mul_legacy_f32 v98, v72, v76
	v_mul_legacy_f32 v79, v82, v76
	v_mul_f32_e32 v77, v83, v76
	v_mul_legacy_f32 v90, v73, v76
	v_mov_b32_e32 v72, v233
	v_mov_b32_e32 v73, v234
	v_mov_b32_e32 v233, v235
	v_mov_b32_e32 v82, v237
	v_mov_b32_e32 v83, v238
	v_mov_b32_e32 v237, v239
	v_pk_add_f32 v[72:73], v[72:73], v[232:233]
	v_pk_add_f32 v[82:83], v[82:83], v[236:237]
	v_mov_b32_e32 v191, v72
	v_mov_b32_e32 v190, v82
	v_mov_b32_e32 v72, v83
	v_pk_add_f32 v[72:73], v[190:191], v[72:73]
	ds_bpermute_b32 v83, v195, v73
	ds_bpermute_b32 v82, v195, v72
	v_cndmask_b32_e64 v102, 0, v88, s[54:55]
	v_mul_legacy_f32 v88, v74, v76
	s_waitcnt lgkmcnt(0)
	v_pk_add_f32 v[72:73], v[72:73], v[82:83]
	v_mul_legacy_f32 v86, v75, v76
	ds_bpermute_b32 v75, v196, v73
	ds_bpermute_b32 v74, v196, v72
	v_mul_legacy_f32 v84, v68, v76
	v_mul_legacy_f32 v80, v69, v76
	s_waitcnt lgkmcnt(0)
	v_pk_add_f32 v[68:69], v[72:73], v[74:75]
	v_mul_f32_e32 v70, v70, v76
	v_pk_fma_f32 v[82:83], v[68:69], s[90:91], v[188:189] op_sel_hi:[1,0,0]
	v_mul_f32_e32 v68, 0x4b800000, v83
	v_cmp_gt_f32_e64 s[52:53], s29, v83
	v_mul_legacy_f32 v76, v71, v76
	v_cndmask_b32_e64 v77, 0, v77, s[50:51]
	v_cndmask_b32_e64 v68, v83, v68, s[52:53]
	v_rsq_f32_e32 v68, v68
	v_cndmask_b32_e64 v78, 0, v70, s[50:51]
	v_cmp_gt_f32_e64 s[50:51], s29, v82
	v_cndmask_b32_e64 v93, 0, v93, s[54:55]
	v_mul_f32_e32 v69, 0x45800000, v68
	v_cndmask_b32_e64 v83, v68, v69, s[52:53]
	v_cndmask_b32_e64 v83, 0, v83, s[48:49]
	v_mul_legacy_f32 v68, v44, v83
	v_mul_f32_e32 v44, v45, v83
	v_mul_f32_e32 v45, 0x4b800000, v82
	v_cndmask_b32_e64 v45, v82, v45, s[50:51]
	v_mul_legacy_f32 v191, v64, v83
	v_rsq_f32_e32 v45, v45
	v_mul_legacy_f32 v75, v65, v83
	v_mul_legacy_f32 v69, v60, v83
	v_mul_legacy_f32 v73, v66, v83
	v_mul_f32_e32 v64, v67, v83
	v_mul_legacy_f32 v67, v61, v83
	v_cndmask_b32_e64 v66, 0, v44, s[48:49]
	v_cndmask_b32_e64 v71, 0, v64, s[48:49]
	v_mul_legacy_f32 v65, v62, v83
	v_mul_legacy_f32 v64, v46, v83
	v_mul_legacy_f32 v61, v63, v83
	v_mul_legacy_f32 v60, v47, v83
	v_mul_f32_e32 v44, 0x45800000, v45
	v_cndmask_b32_e64 v44, v45, v44, s[50:51]
	v_mul_legacy_f32 v190, v56, v83
	v_mul_legacy_f32 v74, v57, v83
	v_cndmask_b32_e64 v44, 0, v44, s[46:47]
	v_mul_legacy_f32 v193, v52, v44
	v_mul_legacy_f32 v72, v58, v83
	v_mul_f32_e32 v56, v59, v83
	v_mul_legacy_f32 v59, v53, v44
	v_mul_legacy_f32 v57, v54, v44
	v_mul_legacy_f32 v55, v55, v44
	v_mul_legacy_f32 v53, v48, v44
	v_mul_legacy_f32 v49, v49, v44
	v_mul_legacy_f32 v192, v40, v44
	v_mul_legacy_f32 v47, v50, v44
	v_mul_f32_e32 v45, v51, v44
	v_mul_legacy_f32 v58, v41, v44
	v_mov_b32_e32 v40, v137
	v_mov_b32_e32 v41, v138
	v_mov_b32_e32 v137, v139
	v_mov_b32_e32 v50, v133
	v_mov_b32_e32 v51, v134
	v_mov_b32_e32 v133, v135
	v_pk_add_f32 v[40:41], v[40:41], v[136:137]
	v_pk_add_f32 v[50:51], v[50:51], v[132:133]
	v_mov_b32_e32 v63, v40
	v_mov_b32_e32 v62, v50
	v_mov_b32_e32 v40, v51
	v_pk_add_f32 v[40:41], v[62:63], v[40:41]
	ds_bpermute_b32 v51, v195, v41
	ds_bpermute_b32 v50, v195, v40
	v_cndmask_b32_e64 v70, 0, v56, s[48:49]
	v_mul_legacy_f32 v56, v42, v44
	s_waitcnt lgkmcnt(0)
	v_pk_add_f32 v[40:41], v[40:41], v[50:51]
	v_mul_legacy_f32 v54, v43, v44
	ds_bpermute_b32 v43, v196, v41
	ds_bpermute_b32 v42, v196, v40
	v_mul_legacy_f32 v52, v28, v44
	v_mul_legacy_f32 v48, v29, v44
	s_waitcnt lgkmcnt(0)
; __device__ __forceinline__ float sigmoidf_(float x) { return __builtin_amdgcn_rcpf(1.0f + __expf(-x)); }
; template <int N> __device__ __forceinline__ float dpp_ror(float v) { return __builtin_bit_cast(float, __builtin_amdgcn_update_dpp(0, __builtin_bit_cast(int, v), 0x120 + N, 0xf, 0xf, false)); }
;     __device__ __forceinline__ void operator()(Acc& acc, const Unit& u, int wr, int wc, int fr, int fq) const {
;     ...
;           for (int q = 0; q < 8; ++q) {
;             const int t = tbase + 16 * q; const bool ok = (t >= 0) && (t < SEQ);
;             float sq = (pq[q][0] + pq[q][1]) + (pq[q][2] + pq[q][3]); sq += bperm_f(ln ^ 16, sq); sq += bperm_f(ln ^ 32, sq);
;             const float rs = rsqrtf(sq * (1.0f / DM) + EPS);
; #pragma unroll
;             for (int bj = 0; bj < 2; ++bj)
; #pragma unroll
;                 for (int n = 0; n < 2; ++n)
; #pragma unroll
;                     for (int i = 0; i < 4; ++i) { const float v = acc[q >> 2][bj][q & 3][n][i]; acc[q >> 2][bj][q & 3][n][i] = ok ? v * rs : 0.f; }
;           }
;           __builtin_amdgcn_sched_barrier(0);
;         }
; #pragma unroll
;         for (int n = 0; n < 2; ++n) {
; #pragma unroll
;             for (int i = 0; i < 4; ++i) {
;                 const int cg_ = ch0 + 4 * n + i, cv_ = DFF + cg_;
;                 const float g0 = cw[cg_], g1 = cw[NUP + cg_], g2 = cw[2 * NUP + cg_], gb = cb[cg_];
;                 const float v0 = cw[cv_], v1 = cw[NUP + cv_], v2 = cw[2 * NUP + cv_], vb = cb[cv_];
;                 float pg1 = 0.f, pg2 = 0.f, pv1 = 0.f, pv2 = 0.f;
; #pragma unroll
;                 for (int q = 0; q < 8; ++q) {
;                     float cgv = acc[q >> 2][0][q & 3][n][i], cvv = acc[q >> 2][1][q & 3][n][i];
;                     asm volatile("" : "+v"(cgv), "+v"(cvv) : "v"(chain));
;                     const float tg1 = dpp_ror<1>(cgv), tg2 = dpp_ror<2>(cgv), tv1 = dpp_ror<1>(cvv), tv2 = dpp_ror<2>(cvv);
;                     const float sg1 = fr >= 1 ? tg1 : pg1, sg2 = fr >= 2 ? tg2 : pg2, sv1 = fr >= 1 ? tv1 : pv1, sv2 = fr >= 2 ? tv2 : pv2;
;                     const float gg = gb + g0 * sg2 + g1 * sg1 + g2 * cgv;
;                     const float vv = vb + v0 * sv2 + v1 * sv1 + v2 * cvv;
;                     chain = gg * sigmoidf_(gg) * vv; acc[q >> 2][0][q & 3][n][i] = chain;
	v_pk_add_f32 v[28:29], v[40:41], v[42:43]
	v_pk_fma_f32 v[28:29], v[28:29], s[90:91], v[188:189] op_sel_hi:[1,0,0]
	v_mul_legacy_f32 v46, v30, v44
	v_mul_f32_e32 v40, 0x4b800000, v29
	v_cmp_gt_f32_e64 s[48:49], s29, v29
	v_mul_legacy_f32 v44, v31, v44
	v_cndmask_b32_e64 v29, v29, v40, s[48:49]
	v_rsq_f32_e32 v29, v29
	v_cndmask_b32_e64 v45, 0, v45, s[46:47]
	v_cmp_gt_f32_e64 s[46:47], s29, v28
	v_mul_f32_e32 v30, 0x45800000, v29
	v_cndmask_b32_e64 v40, v29, v30, s[48:49]
	v_mul_f32_e32 v29, v36, v40
	v_cndmask_b32_e64 v40, 0, v40, s[44:45]
	v_mul_legacy_f32 v36, v12, v40
	v_mul_f32_e32 v12, v13, v40
	v_mul_f32_e32 v13, 0x4b800000, v28
	v_cndmask_b32_e64 v133, 0, v29, s[44:45]
	v_cndmask_b32_e64 v13, v28, v13, s[46:47]
	v_mul_legacy_f32 v63, v37, v40
	v_rsq_f32_e32 v13, v13
	v_mul_legacy_f32 v43, v38, v40
	v_mul_legacy_f32 v39, v39, v40
	v_mul_f32_e32 v29, v32, v40
	v_cndmask_b32_e64 v32, 0, v12, s[44:45]
	v_mul_legacy_f32 v30, v14, v40
	v_mul_legacy_f32 v28, v15, v40
	v_mul_f32_e32 v12, 0x45800000, v13
	v_cndmask_b32_e64 v12, v13, v12, s[46:47]
	v_cndmask_b32_e32 v12, 0, v12, vcc
	v_mul_legacy_f32 v135, v20, v12
	v_mul_legacy_f32 v83, v21, v12
	v_cndmask_b32_e64 v37, 0, v29, s[44:45]
	v_mul_legacy_f32 v51, v22, v12
	v_mul_legacy_f32 v33, v33, v40
	v_mul_legacy_f32 v132, v24, v40
	v_mul_legacy_f32 v41, v23, v12
	v_mul_legacy_f32 v31, v34, v40
	v_mul_f32_e32 v29, v35, v40
	v_mul_legacy_f32 v62, v25, v40
	v_mul_legacy_f32 v35, v16, v12
	v_mul_legacy_f32 v134, v8, v12
	v_mul_legacy_f32 v34, v4, v12
	v_mul_legacy_f32 v42, v26, v40
	v_mul_f32_e32 v24, v27, v40
	v_mul_legacy_f32 v27, v17, v12
	v_mul_legacy_f32 v82, v9, v12
	v_mul_legacy_f32 v26, v5, v12
	v_mul_legacy_f32 v15, v18, v12
	v_mul_legacy_f32 v50, v10, v12
	v_mul_legacy_f32 v14, v6, v12
	v_cndmask_b32_e64 v29, 0, v29, s[44:45]
	v_cndmask_b32_e64 v38, 0, v24, s[44:45]
	v_mul_legacy_f32 v13, v19, v12
	v_mul_legacy_f32 v40, v11, v12
	v_mul_legacy_f32 v12, v7, v12
	v_lshl_or_b32 v4, s34, 7, v2
	v_ashrrev_i32_e32 v5, 31, v4
	v_lshlrev_b64 v[16:17], 2, v[4:5]
	v_lshl_add_u64 v[6:7], s[36:37], 0, v[16:17]
	s_movk_i32 s21, 0x5000
	v_add_co_u32_e32 v8, vcc, s21, v6
	s_mov_b32 s21, 0xb000
	s_nop 0
	v_addc_co_u32_e32 v9, vcc, 0, v7, vcc
	v_add_co_u32_e32 v10, vcc, s21, v6
	v_lshl_add_u64 v[16:17], s[60:61], 0, v[16:17]
	s_nop 0
	v_addc_co_u32_e32 v11, vcc, 0, v7, vcc
	global_load_dword v139, v[6:7], off
	global_load_dword v137, v[8:9], off offset:2048
	global_load_dword v136, v[10:11], off
	global_load_dword v189, v[16:17], off
	v_add_co_u32_e32 v18, vcc, s97, v6
	s_mov_b32 s21, 0xd000
	s_nop 0
	v_addc_co_u32_e32 v19, vcc, 0, v7, vcc
	v_add_co_u32_e32 v22, vcc, s80, v6
	global_load_dword v138, v[18:19], off offset:3072
	s_nop 0
	v_addc_co_u32_e32 v23, vcc, 0, v7, vcc
	v_add_co_u32_e32 v20, vcc, s97, v16
	s_nop 0
	s_nop 0
	v_addc_co_u32_e32 v21, vcc, 0, v17, vcc
	v_add_co_u32_e32 v24, vcc, s21, v6
	global_load_dword v188, v[20:21], off offset:3072
	s_nop 0
	v_addc_co_u32_e32 v25, vcc, 0, v7, vcc
	global_load_dword v229, v[22:23], off offset:1024
	global_load_dword v228, v[24:25], off offset:3072
	s_nop 0
	v_mov_b32_dpp v111, v182 row_ror:1 row_mask:0xf bank_mask:0xf
	v_mov_b32_dpp v121, v182 row_ror:2 row_mask:0xf bank_mask:0xf
	v_cndmask_b32_e64 v183, v111, 0, s[38:39]
	v_cndmask_b32_e64 v155, 0, v121, s[40:41]
	v_mov_b32_dpp v123, v184 row_ror:1 row_mask:0xf bank_mask:0xf
	v_mov_b32_dpp v125, v184 row_ror:2 row_mask:0xf bank_mask:0xf
	v_cndmask_b32_e64 v185, v123, 0, s[38:39]
	v_cndmask_b32_e64 v159, 0, v125, s[40:41]
	s_waitcnt vmcnt(5)
	v_pk_mul_f32 v[182:183], v[136:137], v[182:183]
	s_waitcnt vmcnt(4)
	v_fma_f32 v155, v139, v155, v189
	v_add_f32_e32 v155, v183, v155
	v_add_f32_e32 v155, v182, v155
	v_mul_f32_e32 v161, 0xbfb8aa3b, v155
	v_exp_f32_e32 v161, v161
	v_mov_b32_e32 v183, v136
	v_add_f32_e32 v136, 1.0, v161
	v_rcp_f32_e32 v161, v136
	s_waitcnt vmcnt(2)
	v_fma_f32 v159, v138, v159, v188
	v_mul_f32_e32 v155, v155, v161
	s_waitcnt vmcnt(1)
	v_mov_b32_e32 v136, v229
	s_waitcnt vmcnt(0)
	v_pk_mul_f32 v[184:185], v[228:229], v[184:185]
	v_mov_b32_e32 v182, v228
	v_add_f32_e32 v159, v185, v159
	v_add_f32_e32 v159, v184, v159
	v_mul_f32_e32 v184, v159, v155
	v_mov_b32_dpp v129, v187 row_ror:2 row_mask:0xf bank_mask:0xf
	v_mov_b32_dpp v153, v186 row_ror:2 row_mask:0xf bank_mask:0xf
	v_mov_b32_dpp v127, v187 row_ror:1 row_mask:0xf bank_mask:0xf
	v_mov_b32_dpp v131, v186 row_ror:1 row_mask:0xf bank_mask:0xf
	v_cndmask_b32_e64 v231, v121, v129, s[40:41]
	v_cndmask_b32_e64 v230, v125, v153, s[40:41]
	v_cndmask_b32_e64 v229, v127, v111, s[38:39]
	v_cndmask_b32_e64 v228, v131, v123, s[38:39]
	v_pk_fma_f32 v[230:231], v[138:139], v[230:231], v[188:189]
	v_pk_fma_f32 v[228:229], v[136:137], v[228:229], v[230:231]
	v_pk_fma_f32 v[186:187], v[182:183], v[186:187], v[228:229]
	v_mul_f32_e32 v111, 0xbfb8aa3b, v187
	v_exp_f32_e32 v111, v111
	s_nop 0
	v_add_f32_e32 v111, 1.0, v111
	v_rcp_f32_e32 v111, v111
	s_nop 0
	v_mul_f32_e32 v111, v187, v111
	v_mul_f32_e32 v185, v186, v111
	v_mov_b32_dpp v123, v115 row_ror:2 row_mask:0xf bank_mask:0xf
	v_mov_b32_dpp v155, v114 row_ror:2 row_mask:0xf bank_mask:0xf
	v_mov_b32_dpp v121, v115 row_ror:1 row_mask:0xf bank_mask:0xf
	v_mov_b32_dpp v125, v114 row_ror:1 row_mask:0xf bank_mask:0xf
	v_cndmask_b32_e64 v229, v129, v123, s[40:41]
	v_cndmask_b32_e64 v228, v153, v155, s[40:41]
	v_cndmask_b32_e64 v187, v121, v127, s[38:39]
	v_cndmask_b32_e64 v186, v125, v131, s[38:39]
	v_pk_fma_f32 v[228:229], v[138:139], v[228:229], v[188:189]
	v_pk_fma_f32 v[186:187], v[136:137], v[186:187], v[228:229]
	v_pk_fma_f32 v[114:115], v[182:183], v[114:115], v[186:187]
; __device__ __forceinline__ float sigmoidf_(float x) { return __builtin_amdgcn_rcpf(1.0f + __expf(-x)); }
; template <int N> __device__ __forceinline__ float dpp_ror(float v) { return __builtin_bit_cast(float, __builtin_amdgcn_update_dpp(0, __builtin_bit_cast(int, v), 0x120 + N, 0xf, 0xf, false)); }
;     __device__ __forceinline__ void operator()(Acc& acc, const Unit& u, int wr, int wc, int fr, int fq) const {
;     ...
;             for (int i = 0; i < 4; ++i) {
;                 const int cg_ = ch0 + 4 * n + i, cv_ = DFF + cg_;
;                 const float g0 = cw[cg_], g1 = cw[NUP + cg_], g2 = cw[2 * NUP + cg_], gb = cb[cg_];
;                 const float v0 = cw[cv_], v1 = cw[NUP + cv_], v2 = cw[2 * NUP + cv_], vb = cb[cv_];
;                 float pg1 = 0.f, pg2 = 0.f, pv1 = 0.f, pv2 = 0.f;
; #pragma unroll
;                 for (int q = 0; q < 8; ++q) {
;                     float cgv = acc[q >> 2][0][q & 3][n][i], cvv = acc[q >> 2][1][q & 3][n][i];
;                     asm volatile("" : "+v"(cgv), "+v"(cvv) : "v"(chain));
;                     const float tg1 = dpp_ror<1>(cgv), tg2 = dpp_ror<2>(cgv), tv1 = dpp_ror<1>(cvv), tv2 = dpp_ror<2>(cvv);
;                     const float sg1 = fr >= 1 ? tg1 : pg1, sg2 = fr >= 2 ? tg2 : pg2, sv1 = fr >= 1 ? tv1 : pv1, sv2 = fr >= 2 ? tv2 : pv2;
;                     const float gg = gb + g0 * sg2 + g1 * sg1 + g2 * cgv;
;                     const float vv = vb + v0 * sv2 + v1 * sv1 + v2 * cvv;
;                     chain = gg * sigmoidf_(gg) * vv; acc[q >> 2][0][q & 3][n][i] = chain;
;                     pg1 = tg1; pg2 = tg2; pv1 = tv1; pv2 = tv2;
;                 }
	v_mul_f32_e32 v111, 0xbfb8aa3b, v115
	v_exp_f32_e32 v111, v111
	s_nop 0
	v_add_f32_e32 v111, 1.0, v111
	v_rcp_f32_e32 v111, v111
	s_nop 0
	v_mul_f32_e32 v111, v115, v111
	v_mul_f32_e32 v186, v114, v111
	v_mov_b32_dpp v129, v99 row_ror:2 row_mask:0xf bank_mask:0xf
	v_mov_b32_dpp v153, v98 row_ror:2 row_mask:0xf bank_mask:0xf
	v_mov_b32_dpp v127, v99 row_ror:1 row_mask:0xf bank_mask:0xf
	v_mov_b32_dpp v131, v98 row_ror:1 row_mask:0xf bank_mask:0xf
	v_cndmask_b32_e64 v229, v123, v129, s[40:41]
	v_cndmask_b32_e64 v228, v155, v153, s[40:41]
	v_cndmask_b32_e64 v115, v127, v121, s[38:39]
	v_cndmask_b32_e64 v114, v131, v125, s[38:39]
	v_pk_fma_f32 v[228:229], v[138:139], v[228:229], v[188:189]
	v_pk_fma_f32 v[114:115], v[136:137], v[114:115], v[228:229]
	v_pk_fma_f32 v[98:99], v[182:183], v[98:99], v[114:115]
	v_mul_f32_e32 v111, 0xbfb8aa3b, v99
	v_exp_f32_e32 v111, v111
	s_nop 0
	v_add_f32_e32 v111, 1.0, v111
	v_rcp_f32_e32 v111, v111
	s_nop 0
	v_mul_f32_e32 v99, v99, v111
	v_mul_f32_e32 v187, v98, v99
	v_mov_b32_dpp v123, v191 row_ror:2 row_mask:0xf bank_mask:0xf
	v_mov_b32_dpp v155, v190 row_ror:2 row_mask:0xf bank_mask:0xf
	v_mov_b32_dpp v121, v191 row_ror:1 row_mask:0xf bank_mask:0xf
	v_mov_b32_dpp v125, v190 row_ror:1 row_mask:0xf bank_mask:0xf
	v_cndmask_b32_e64 v115, v129, v123, s[40:41]
	v_cndmask_b32_e64 v114, v153, v155, s[40:41]
	v_cndmask_b32_e64 v99, v121, v127, s[38:39]
	v_cndmask_b32_e64 v98, v125, v131, s[38:39]
	v_pk_fma_f32 v[114:115], v[138:139], v[114:115], v[188:189]
	v_pk_fma_f32 v[98:99], v[136:137], v[98:99], v[114:115]
	v_pk_fma_f32 v[98:99], v[182:183], v[190:191], v[98:99]
	v_mul_f32_e32 v111, 0xbfb8aa3b, v99
	v_exp_f32_e32 v111, v111
	s_nop 0
	v_add_f32_e32 v111, 1.0, v111
	v_rcp_f32_e32 v111, v111
	s_nop 0
	v_mul_f32_e32 v99, v99, v111
	v_mul_f32_e32 v190, v98, v99
	v_mov_b32_dpp v129, v193 row_ror:2 row_mask:0xf bank_mask:0xf
	v_mov_b32_dpp v153, v192 row_ror:2 row_mask:0xf bank_mask:0xf
	v_mov_b32_dpp v127, v193 row_ror:1 row_mask:0xf bank_mask:0xf
	v_mov_b32_dpp v131, v192 row_ror:1 row_mask:0xf bank_mask:0xf
	v_cndmask_b32_e64 v115, v123, v129, s[40:41]
	v_cndmask_b32_e64 v114, v155, v153, s[40:41]
	v_cndmask_b32_e64 v99, v127, v121, s[38:39]
	v_cndmask_b32_e64 v98, v131, v125, s[38:39]
	v_pk_fma_f32 v[114:115], v[138:139], v[114:115], v[188:189]
	v_pk_fma_f32 v[98:99], v[136:137], v[98:99], v[114:115]
	v_pk_fma_f32 v[98:99], v[182:183], v[192:193], v[98:99]
	v_mul_f32_e32 v111, 0xbfb8aa3b, v99
	v_exp_f32_e32 v111, v111
	s_nop 0
	v_add_f32_e32 v111, 1.0, v111
	v_rcp_f32_e32 v111, v111
	s_nop 0
	v_mul_f32_e32 v99, v99, v111
	v_mul_f32_e32 v191, v98, v99
	v_mov_b32_dpp v123, v133 row_ror:2 row_mask:0xf bank_mask:0xf
	v_mov_b32_dpp v155, v132 row_ror:2 row_mask:0xf bank_mask:0xf
	v_mov_b32_dpp v121, v133 row_ror:1 row_mask:0xf bank_mask:0xf
	v_mov_b32_dpp v125, v132 row_ror:1 row_mask:0xf bank_mask:0xf
	v_cndmask_b32_e64 v115, v129, v123, s[40:41]
	v_cndmask_b32_e64 v114, v153, v155, s[40:41]
	v_cndmask_b32_e64 v99, v121, v127, s[38:39]
	v_cndmask_b32_e64 v98, v125, v131, s[38:39]
	v_pk_fma_f32 v[114:115], v[138:139], v[114:115], v[188:189]
	v_pk_fma_f32 v[98:99], v[136:137], v[98:99], v[114:115]
	v_pk_fma_f32 v[98:99], v[182:183], v[132:133], v[98:99]
	v_mul_f32_e32 v111, 0xbfb8aa3b, v99
	v_exp_f32_e32 v111, v111
	s_nop 0
	v_add_f32_e32 v111, 1.0, v111
	v_rcp_f32_e32 v111, v111
	s_nop 0
	v_mul_f32_e32 v99, v99, v111
	v_mul_f32_e32 v192, v98, v99
	v_mov_b32_dpp v114, v135 row_ror:1 row_mask:0xf bank_mask:0xf
	v_mov_b32_dpp v115, v135 row_ror:2 row_mask:0xf bank_mask:0xf
	v_mov_b32_dpp v129, v134 row_ror:2 row_mask:0xf bank_mask:0xf
	v_mov_b32_dpp v127, v134 row_ror:1 row_mask:0xf bank_mask:0xf
	v_cndmask_b32_e64 v99, v114, v121, s[38:39]
	v_cndmask_b32_e64 v115, v123, v115, s[40:41]
	v_cndmask_b32_e64 v114, v155, v129, s[40:41]
	v_cndmask_b32_e64 v98, v127, v125, s[38:39]
	v_pk_fma_f32 v[114:115], v[138:139], v[114:115], v[188:189]
	s_nop 0
	v_pk_fma_f32 v[98:99], v[136:137], v[98:99], v[114:115]
	s_nop 0
	v_pk_fma_f32 v[98:99], v[182:183], v[134:135], v[98:99]
	s_nop 0
	v_mul_f32_e32 v111, 0xbfb8aa3b, v99
	v_exp_f32_e32 v111, v111
	s_nop 0
	v_add_f32_e32 v111, 1.0, v111
	v_rcp_f32_e32 v111, v111
	s_nop 0
	v_mul_f32_e32 v99, v99, v111
	v_mul_f32_e32 v136, v98, v99
	global_load_dword v115, v[6:7], off offset:4
	global_load_dword v99, v[8:9], off offset:2052
	global_load_dword v98, v[10:11], off offset:4
	global_load_dword v133, v[16:17], off offset:4
	global_load_dword v132, v[20:21], off offset:3076
	global_load_dword v114, v[18:19], off offset:3076
	global_load_dword v139, v[22:23], off offset:1028
	global_load_dword v138, v[24:25], off offset:3076
	v_mov_b32_dpp v111, v176 row_ror:1 row_mask:0xf bank_mask:0xf
	v_mov_b32_dpp v121, v176 row_ror:2 row_mask:0xf bank_mask:0xf
	v_cndmask_b32_e64 v177, v111, 0, s[38:39]
	v_cndmask_b32_e64 v134, 0, v121, s[40:41]
	v_mov_b32_dpp v123, v178 row_ror:1 row_mask:0xf bank_mask:0xf
	v_cndmask_b32_e64 v179, v123, 0, s[38:39]
	v_mov_b32_dpp v125, v178 row_ror:2 row_mask:0xf bank_mask:0xf
	v_cndmask_b32_e64 v137, 0, v125, s[40:41]
	s_waitcnt vmcnt(4)
	v_fma_f32 v155, v115, v134, v133
	v_pk_mul_f32 v[134:135], v[98:99], v[176:177]
	s_waitcnt vmcnt(2)
	v_fma_f32 v137, v114, v137, v132
	v_add_f32_e32 v135, v135, v155
	v_add_f32_e32 v155, v134, v135
	v_mul_f32_e32 v134, 0xbfb8aa3b, v155
	v_exp_f32_e32 v159, v134
	v_mov_b32_e32 v135, v98
	s_waitcnt vmcnt(0)
; __device__ __forceinline__ float sigmoidf_(float x) { return __builtin_amdgcn_rcpf(1.0f + __expf(-x)); }
; template <int N> __device__ __forceinline__ float dpp_ror(float v) { return __builtin_bit_cast(float, __builtin_amdgcn_update_dpp(0, __builtin_bit_cast(int, v), 0x120 + N, 0xf, 0xf, false)); }
;     __device__ __forceinline__ void operator()(Acc& acc, const Unit& u, int wr, int wc, int fr, int fq) const {
;     ...
;             for (int i = 0; i < 4; ++i) {
;                 const int cg_ = ch0 + 4 * n + i, cv_ = DFF + cg_;
;                 const float g0 = cw[cg_], g1 = cw[NUP + cg_], g2 = cw[2 * NUP + cg_], gb = cb[cg_];
;                 const float v0 = cw[cv_], v1 = cw[NUP + cv_], v2 = cw[2 * NUP + cv_], vb = cb[cv_];
;                 float pg1 = 0.f, pg2 = 0.f, pv1 = 0.f, pv2 = 0.f;
; #pragma unroll
;                 for (int q = 0; q < 8; ++q) {
;                     float cgv = acc[q >> 2][0][q & 3][n][i], cvv = acc[q >> 2][1][q & 3][n][i];
;                     asm volatile("" : "+v"(cgv), "+v"(cvv) : "v"(chain));
;                     const float tg1 = dpp_ror<1>(cgv), tg2 = dpp_ror<2>(cgv), tv1 = dpp_ror<1>(cvv), tv2 = dpp_ror<2>(cvv);
;                     const float sg1 = fr >= 1 ? tg1 : pg1, sg2 = fr >= 2 ? tg2 : pg2, sv1 = fr >= 1 ? tv1 : pv1, sv2 = fr >= 2 ? tv2 : pv2;
;                     const float gg = gb + g0 * sg2 + g1 * sg1 + g2 * cgv;
;                     const float vv = vb + v0 * sv2 + v1 * sv1 + v2 * cvv;
;                     chain = gg * sigmoidf_(gg) * vv; acc[q >> 2][0][q & 3][n][i] = chain;
;                     pg1 = tg1; pg2 = tg2; pv1 = tv1; pv2 = tv2;
;                 }
	v_pk_mul_f32 v[176:177], v[138:139], v[178:179]
	v_mov_b32_e32 v134, v138
	v_add_f32_e32 v98, 1.0, v159
	v_rcp_f32_e32 v138, v98
	v_add_f32_e32 v137, v177, v137
	v_add_f32_e32 v137, v176, v137
	v_mov_b32_e32 v98, v139
	v_mul_f32_e32 v138, v155, v138
	v_mul_f32_e32 v137, v137, v138
	v_mov_b32_dpp v129, v181 row_ror:2 row_mask:0xf bank_mask:0xf
	v_mov_b32_dpp v153, v180 row_ror:2 row_mask:0xf bank_mask:0xf
	v_mov_b32_dpp v127, v181 row_ror:1 row_mask:0xf bank_mask:0xf
	v_mov_b32_dpp v131, v180 row_ror:1 row_mask:0xf bank_mask:0xf
	v_cndmask_b32_e64 v177, v121, v129, s[40:41]
	v_cndmask_b32_e64 v176, v125, v153, s[40:41]
	v_cndmask_b32_e64 v139, v127, v111, s[38:39]
	v_cndmask_b32_e64 v138, v131, v123, s[38:39]
	v_pk_fma_f32 v[176:177], v[114:115], v[176:177], v[132:133]
	v_pk_fma_f32 v[138:139], v[98:99], v[138:139], v[176:177]
	v_pk_fma_f32 v[138:139], v[134:135], v[180:181], v[138:139]
	v_mul_f32_e32 v111, 0xbfb8aa3b, v139
	v_exp_f32_e32 v111, v111
	s_nop 0
	v_add_f32_e32 v111, 1.0, v111
	v_rcp_f32_e32 v111, v111
	s_nop 0
	v_mul_f32_e32 v111, v139, v111
	v_mul_f32_e32 v138, v138, v111
	v_mov_b32_dpp v123, v107 row_ror:2 row_mask:0xf bank_mask:0xf
	v_mov_b32_dpp v155, v106 row_ror:2 row_mask:0xf bank_mask:0xf
	v_mov_b32_dpp v121, v107 row_ror:1 row_mask:0xf bank_mask:0xf
	v_mov_b32_dpp v125, v106 row_ror:1 row_mask:0xf bank_mask:0xf
	v_cndmask_b32_e64 v179, v129, v123, s[40:41]
	v_cndmask_b32_e64 v178, v153, v155, s[40:41]
	v_cndmask_b32_e64 v177, v121, v127, s[38:39]
	v_cndmask_b32_e64 v176, v125, v131, s[38:39]
	v_pk_fma_f32 v[178:179], v[114:115], v[178:179], v[132:133]
	v_pk_fma_f32 v[176:177], v[98:99], v[176:177], v[178:179]
	v_pk_fma_f32 v[106:107], v[134:135], v[106:107], v[176:177]
	v_mul_f32_e32 v111, 0xbfb8aa3b, v107
	v_exp_f32_e32 v111, v111
	s_nop 0
	v_add_f32_e32 v111, 1.0, v111
	v_rcp_f32_e32 v111, v111
	s_nop 0
	v_mul_f32_e32 v107, v107, v111
	v_mul_f32_e32 v106, v106, v107
	v_mov_b32_dpp v129, v91 row_ror:2 row_mask:0xf bank_mask:0xf
	v_mov_b32_dpp v139, v90 row_ror:2 row_mask:0xf bank_mask:0xf
	v_mov_b32_dpp v127, v91 row_ror:1 row_mask:0xf bank_mask:0xf
	v_mov_b32_dpp v131, v90 row_ror:1 row_mask:0xf bank_mask:0xf
	v_cndmask_b32_e64 v179, v123, v129, s[40:41]
	v_cndmask_b32_e64 v178, v155, v139, s[40:41]
	v_cndmask_b32_e64 v177, v127, v121, s[38:39]
	v_cndmask_b32_e64 v176, v131, v125, s[38:39]
	v_pk_fma_f32 v[178:179], v[114:115], v[178:179], v[132:133]
	v_pk_fma_f32 v[176:177], v[98:99], v[176:177], v[178:179]
	v_pk_fma_f32 v[90:91], v[134:135], v[90:91], v[176:177]
	v_mul_f32_e32 v107, 0xbfb8aa3b, v91
	v_exp_f32_e32 v107, v107
	s_nop 0
	v_add_f32_e32 v107, 1.0, v107
	v_rcp_f32_e32 v107, v107
	s_nop 0
	v_mul_f32_e32 v91, v91, v107
	v_mul_f32_e32 v90, v90, v91
	v_mov_b32_dpp v121, v75 row_ror:2 row_mask:0xf bank_mask:0xf
	v_mov_b32_dpp v125, v74 row_ror:2 row_mask:0xf bank_mask:0xf
	v_mov_b32_dpp v111, v75 row_ror:1 row_mask:0xf bank_mask:0xf
	v_mov_b32_dpp v123, v74 row_ror:1 row_mask:0xf bank_mask:0xf
	v_cndmask_b32_e64 v179, v129, v121, s[40:41]
	v_cndmask_b32_e64 v178, v139, v125, s[40:41]
	v_cndmask_b32_e64 v177, v111, v127, s[38:39]
	v_cndmask_b32_e64 v176, v123, v131, s[38:39]
	v_pk_fma_f32 v[178:179], v[114:115], v[178:179], v[132:133]
	v_pk_fma_f32 v[176:177], v[98:99], v[176:177], v[178:179]
	v_pk_fma_f32 v[74:75], v[134:135], v[74:75], v[176:177]
	v_mul_f32_e32 v91, 0xbfb8aa3b, v75
	v_exp_f32_e32 v91, v91
	s_nop 0
	v_add_f32_e32 v91, 1.0, v91
	v_rcp_f32_e32 v91, v91
	s_nop 0
	v_mul_f32_e32 v75, v75, v91
	v_mul_f32_e32 v91, v74, v75
	v_mov_b32_dpp v129, v59 row_ror:2 row_mask:0xf bank_mask:0xf
	v_mov_b32_dpp v139, v58 row_ror:2 row_mask:0xf bank_mask:0xf
	v_mov_b32_dpp v127, v59 row_ror:1 row_mask:0xf bank_mask:0xf
	v_mov_b32_dpp v131, v58 row_ror:1 row_mask:0xf bank_mask:0xf
	v_cndmask_b32_e64 v177, v121, v129, s[40:41]
	v_cndmask_b32_e64 v176, v125, v139, s[40:41]
	v_cndmask_b32_e64 v75, v127, v111, s[38:39]
	v_cndmask_b32_e64 v74, v131, v123, s[38:39]
	v_pk_fma_f32 v[176:177], v[114:115], v[176:177], v[132:133]
	v_pk_fma_f32 v[74:75], v[98:99], v[74:75], v[176:177]
	v_pk_fma_f32 v[58:59], v[134:135], v[58:59], v[74:75]
	v_mul_f32_e32 v74, 0xbfb8aa3b, v59
	v_exp_f32_e32 v74, v74
	s_nop 0
	v_add_f32_e32 v74, 1.0, v74
	v_rcp_f32_e32 v74, v74
	s_nop 0
	v_mul_f32_e32 v59, v59, v74
	v_mul_f32_e32 v107, v58, v59
	v_mov_b32_dpp v121, v63 row_ror:2 row_mask:0xf bank_mask:0xf
	v_mov_b32_dpp v125, v62 row_ror:2 row_mask:0xf bank_mask:0xf
	v_mov_b32_dpp v111, v63 row_ror:1 row_mask:0xf bank_mask:0xf
	v_mov_b32_dpp v123, v62 row_ror:1 row_mask:0xf bank_mask:0xf
	v_cndmask_b32_e64 v75, v129, v121, s[40:41]
	v_cndmask_b32_e64 v74, v139, v125, s[40:41]
	v_cndmask_b32_e64 v59, v111, v127, s[38:39]
	v_cndmask_b32_e64 v58, v123, v131, s[38:39]
	v_pk_fma_f32 v[74:75], v[114:115], v[74:75], v[132:133]
	v_pk_fma_f32 v[58:59], v[98:99], v[58:59], v[74:75]
	v_pk_fma_f32 v[58:59], v[134:135], v[62:63], v[58:59]
	v_mul_f32_e32 v62, 0xbfb8aa3b, v59
	v_exp_f32_e32 v62, v62
	s_nop 0
	v_add_f32_e32 v62, 1.0, v62
	v_rcp_f32_e32 v62, v62
	s_nop 0
	v_mul_f32_e32 v59, v59, v62
	v_mul_f32_e32 v139, v58, v59
	v_mov_b32_dpp v63, v83 row_ror:1 row_mask:0xf bank_mask:0xf
	v_mov_b32_dpp v74, v83 row_ror:2 row_mask:0xf bank_mask:0xf
	v_mov_b32_dpp v127, v82 row_ror:2 row_mask:0xf bank_mask:0xf
	v_mov_b32_dpp v75, v82 row_ror:1 row_mask:0xf bank_mask:0xf
	v_cndmask_b32_e64 v59, v63, v111, s[38:39]
	v_cndmask_b32_e64 v63, v121, v74, s[40:41]
	v_cndmask_b32_e64 v62, v125, v127, s[40:41]
	v_cndmask_b32_e64 v58, v75, v123, s[38:39]
	v_pk_fma_f32 v[62:63], v[114:115], v[62:63], v[132:133]
	s_nop 0
	v_pk_fma_f32 v[58:59], v[98:99], v[58:59], v[62:63]
	s_nop 0
	v_pk_fma_f32 v[58:59], v[134:135], v[82:83], v[58:59]
	s_nop 0
	v_mul_f32_e32 v62, 0xbfb8aa3b, v59
	v_exp_f32_e32 v62, v62
	s_nop 0
	v_add_f32_e32 v62, 1.0, v62
	v_rcp_f32_e32 v62, v62
	s_nop 0
	v_mul_f32_e32 v59, v59, v62
	v_mul_f32_e32 v98, v58, v59
	global_load_dword v63, v[6:7], off offset:8
	global_load_dword v59, v[8:9], off offset:2056
	global_load_dword v58, v[10:11], off offset:8
	global_load_dword v75, v[16:17], off offset:8
	global_load_dword v74, v[20:21], off offset:3080
	global_load_dword v62, v[18:19], off offset:3080
	global_load_dword v115, v[22:23], off offset:1032
	global_load_dword v114, v[24:25], off offset:3080
	v_mov_b32_dpp v111, v160 row_ror:1 row_mask:0xf bank_mask:0xf
	v_mov_b32_dpp v121, v160 row_ror:2 row_mask:0xf bank_mask:0xf
	v_cndmask_b32_e64 v161, v111, 0, s[38:39]
	v_cndmask_b32_e64 v82, 0, v121, s[40:41]
	v_mov_b32_dpp v123, v162 row_ror:1 row_mask:0xf bank_mask:0xf
	v_cndmask_b32_e64 v163, v123, 0, s[38:39]
	v_mov_b32_dpp v125, v162 row_ror:2 row_mask:0xf bank_mask:0xf
	v_cndmask_b32_e64 v99, 0, v125, s[40:41]
	s_waitcnt vmcnt(4)
; __device__ __forceinline__ float sigmoidf_(float x) { return __builtin_amdgcn_rcpf(1.0f + __expf(-x)); }
; template <int N> __device__ __forceinline__ float dpp_ror(float v) { return __builtin_bit_cast(float, __builtin_amdgcn_update_dpp(0, __builtin_bit_cast(int, v), 0x120 + N, 0xf, 0xf, false)); }
;     __device__ __forceinline__ void operator()(Acc& acc, const Unit& u, int wr, int wc, int fr, int fq) const {
;     ...
;             for (int i = 0; i < 4; ++i) {
;                 const int cg_ = ch0 + 4 * n + i, cv_ = DFF + cg_;
;                 const float g0 = cw[cg_], g1 = cw[NUP + cg_], g2 = cw[2 * NUP + cg_], gb = cb[cg_];
;                 const float v0 = cw[cv_], v1 = cw[NUP + cv_], v2 = cw[2 * NUP + cv_], vb = cb[cv_];
;                 float pg1 = 0.f, pg2 = 0.f, pv1 = 0.f, pv2 = 0.f;
; #pragma unroll
;                 for (int q = 0; q < 8; ++q) {
;                     float cgv = acc[q >> 2][0][q & 3][n][i], cvv = acc[q >> 2][1][q & 3][n][i];
;                     asm volatile("" : "+v"(cgv), "+v"(cvv) : "v"(chain));
;                     const float tg1 = dpp_ror<1>(cgv), tg2 = dpp_ror<2>(cgv), tv1 = dpp_ror<1>(cvv), tv2 = dpp_ror<2>(cvv);
;                     const float sg1 = fr >= 1 ? tg1 : pg1, sg2 = fr >= 2 ? tg2 : pg2, sv1 = fr >= 1 ? tv1 : pv1, sv2 = fr >= 2 ? tv2 : pv2;
;                     const float gg = gb + g0 * sg2 + g1 * sg1 + g2 * cgv;
;                     const float vv = vb + v0 * sv2 + v1 * sv1 + v2 * cvv;
;                     chain = gg * sigmoidf_(gg) * vv; acc[q >> 2][0][q & 3][n][i] = chain;
;                     pg1 = tg1; pg2 = tg2; pv1 = tv1; pv2 = tv2;
;                 }
	v_fma_f32 v132, v63, v82, v75
	v_pk_mul_f32 v[82:83], v[58:59], v[160:161]
	s_waitcnt vmcnt(2)
	v_fma_f32 v99, v62, v99, v74
	v_add_f32_e32 v83, v83, v132
	v_add_f32_e32 v135, v82, v83
	v_mul_f32_e32 v82, 0xbfb8aa3b, v135
	v_exp_f32_e32 v153, v82
	v_mov_b32_e32 v83, v58
	s_waitcnt vmcnt(0)
	v_pk_mul_f32 v[132:133], v[114:115], v[162:163]
	v_mov_b32_e32 v82, v114
	v_add_f32_e32 v58, 1.0, v153
	v_rcp_f32_e32 v114, v58
	v_add_f32_e32 v99, v133, v99
	v_add_f32_e32 v99, v132, v99
	v_mov_b32_e32 v58, v115
	v_mul_f32_e32 v114, v135, v114
	v_mul_f32_e32 v99, v99, v114
	v_mov_b32_dpp v129, v175 row_ror:2 row_mask:0xf bank_mask:0xf
	v_mov_b32_dpp v134, v174 row_ror:2 row_mask:0xf bank_mask:0xf
	v_mov_b32_dpp v127, v175 row_ror:1 row_mask:0xf bank_mask:0xf
	v_mov_b32_dpp v131, v174 row_ror:1 row_mask:0xf bank_mask:0xf
	v_cndmask_b32_e64 v133, v121, v129, s[40:41]
	v_cndmask_b32_e64 v132, v125, v134, s[40:41]
	v_cndmask_b32_e64 v115, v127, v111, s[38:39]
	v_cndmask_b32_e64 v114, v131, v123, s[38:39]
	v_pk_fma_f32 v[132:133], v[62:63], v[132:133], v[74:75]
	v_pk_fma_f32 v[114:115], v[58:59], v[114:115], v[132:133]
	v_pk_fma_f32 v[114:115], v[82:83], v[174:175], v[114:115]
	v_mul_f32_e32 v111, 0xbfb8aa3b, v115
	v_exp_f32_e32 v111, v111
	s_nop 0
	v_add_f32_e32 v111, 1.0, v111
	v_rcp_f32_e32 v111, v111
	s_nop 0
	v_mul_f32_e32 v111, v115, v111
	v_mul_f32_e32 v114, v114, v111
	v_mov_b32_dpp v123, v105 row_ror:2 row_mask:0xf bank_mask:0xf
	v_mov_b32_dpp v153, v104 row_ror:2 row_mask:0xf bank_mask:0xf
	v_mov_b32_dpp v121, v105 row_ror:1 row_mask:0xf bank_mask:0xf
	v_mov_b32_dpp v125, v104 row_ror:1 row_mask:0xf bank_mask:0xf
	v_cndmask_b32_e64 v135, v129, v123, s[40:41]
	v_cndmask_b32_e64 v134, v134, v153, s[40:41]
	v_cndmask_b32_e64 v133, v121, v127, s[38:39]
	v_cndmask_b32_e64 v132, v125, v131, s[38:39]
	v_pk_fma_f32 v[134:135], v[62:63], v[134:135], v[74:75]
	v_pk_fma_f32 v[132:133], v[58:59], v[132:133], v[134:135]
	v_pk_fma_f32 v[104:105], v[82:83], v[104:105], v[132:133]
	v_mul_f32_e32 v111, 0xbfb8aa3b, v105
	v_exp_f32_e32 v111, v111
	s_nop 0
	v_add_f32_e32 v111, 1.0, v111
	v_rcp_f32_e32 v111, v111
	s_nop 0
	v_mul_f32_e32 v105, v105, v111
	v_mul_f32_e32 v104, v104, v105
	v_mov_b32_dpp v127, v89 row_ror:2 row_mask:0xf bank_mask:0xf
	v_mov_b32_dpp v131, v88 row_ror:2 row_mask:0xf bank_mask:0xf
	v_mov_b32_dpp v115, v89 row_ror:1 row_mask:0xf bank_mask:0xf
	v_mov_b32_dpp v129, v88 row_ror:1 row_mask:0xf bank_mask:0xf
	v_cndmask_b32_e64 v135, v123, v127, s[40:41]
	v_cndmask_b32_e64 v134, v153, v131, s[40:41]
	v_cndmask_b32_e64 v133, v115, v121, s[38:39]
	v_cndmask_b32_e64 v132, v129, v125, s[38:39]
	v_pk_fma_f32 v[134:135], v[62:63], v[134:135], v[74:75]
	v_pk_fma_f32 v[132:133], v[58:59], v[132:133], v[134:135]
	v_pk_fma_f32 v[88:89], v[82:83], v[88:89], v[132:133]
	v_mul_f32_e32 v105, 0xbfb8aa3b, v89
	v_exp_f32_e32 v105, v105
	s_nop 0
	v_add_f32_e32 v105, 1.0, v105
	v_rcp_f32_e32 v105, v105
	s_nop 0
	v_mul_f32_e32 v89, v89, v105
	v_mul_f32_e32 v88, v88, v89
	v_mov_b32_dpp v121, v73 row_ror:2 row_mask:0xf bank_mask:0xf
	v_mov_b32_dpp v125, v72 row_ror:2 row_mask:0xf bank_mask:0xf
	v_mov_b32_dpp v111, v73 row_ror:1 row_mask:0xf bank_mask:0xf
	v_mov_b32_dpp v123, v72 row_ror:1 row_mask:0xf bank_mask:0xf
	v_cndmask_b32_e64 v135, v127, v121, s[40:41]
	v_cndmask_b32_e64 v134, v131, v125, s[40:41]
	v_cndmask_b32_e64 v133, v111, v115, s[38:39]
	v_cndmask_b32_e64 v132, v123, v129, s[38:39]
	v_pk_fma_f32 v[134:135], v[62:63], v[134:135], v[74:75]
	v_pk_fma_f32 v[132:133], v[58:59], v[132:133], v[134:135]
	v_pk_fma_f32 v[72:73], v[82:83], v[72:73], v[132:133]
	v_mul_f32_e32 v89, 0xbfb8aa3b, v73
	v_exp_f32_e32 v89, v89
	s_nop 0
	v_add_f32_e32 v89, 1.0, v89
	v_rcp_f32_e32 v89, v89
	s_nop 0
	v_mul_f32_e32 v73, v73, v89
	v_mul_f32_e32 v72, v72, v73
	v_mov_b32_dpp v115, v57 row_ror:2 row_mask:0xf bank_mask:0xf
	v_mov_b32_dpp v129, v56 row_ror:2 row_mask:0xf bank_mask:0xf
	v_mov_b32_dpp v105, v57 row_ror:1 row_mask:0xf bank_mask:0xf
	v_mov_b32_dpp v127, v56 row_ror:1 row_mask:0xf bank_mask:0xf
	v_cndmask_b32_e64 v135, v121, v115, s[40:41]
	v_cndmask_b32_e64 v134, v125, v129, s[40:41]
	v_cndmask_b32_e64 v133, v105, v111, s[38:39]
	v_cndmask_b32_e64 v132, v127, v123, s[38:39]
	v_pk_fma_f32 v[134:135], v[62:63], v[134:135], v[74:75]
	v_pk_fma_f32 v[132:133], v[58:59], v[132:133], v[134:135]
	v_pk_fma_f32 v[56:57], v[82:83], v[56:57], v[132:133]
	v_mul_f32_e32 v73, 0xbfb8aa3b, v57
	v_exp_f32_e32 v73, v73
	s_nop 0
	v_add_f32_e32 v73, 1.0, v73
	v_rcp_f32_e32 v73, v73
	s_nop 0
	v_mul_f32_e32 v57, v57, v73
	v_mul_f32_e32 v73, v56, v57
	v_mov_b32_dpp v121, v43 row_ror:2 row_mask:0xf bank_mask:0xf
	v_mov_b32_dpp v125, v42 row_ror:2 row_mask:0xf bank_mask:0xf
	v_mov_b32_dpp v111, v43 row_ror:1 row_mask:0xf bank_mask:0xf
	v_mov_b32_dpp v123, v42 row_ror:1 row_mask:0xf bank_mask:0xf
	v_cndmask_b32_e64 v133, v115, v121, s[40:41]
	v_cndmask_b32_e64 v132, v129, v125, s[40:41]
	v_cndmask_b32_e64 v57, v111, v105, s[38:39]
	v_cndmask_b32_e64 v56, v123, v127, s[38:39]
	v_pk_fma_f32 v[132:133], v[62:63], v[132:133], v[74:75]
	v_pk_fma_f32 v[56:57], v[58:59], v[56:57], v[132:133]
	v_pk_fma_f32 v[42:43], v[82:83], v[42:43], v[56:57]
	v_mul_f32_e32 v56, 0xbfb8aa3b, v43
	v_exp_f32_e32 v56, v56
	s_nop 0
	v_add_f32_e32 v56, 1.0, v56
	v_rcp_f32_e32 v56, v56
	s_nop 0
	v_mul_f32_e32 v43, v43, v56
	v_mul_f32_e32 v89, v42, v43
	v_mov_b32_dpp v57, v51 row_ror:1 row_mask:0xf bank_mask:0xf
	v_mov_b32_dpp v105, v51 row_ror:2 row_mask:0xf bank_mask:0xf
	v_mov_b32_dpp v127, v50 row_ror:2 row_mask:0xf bank_mask:0xf
	v_mov_b32_dpp v115, v50 row_ror:1 row_mask:0xf bank_mask:0xf
	v_cndmask_b32_e64 v43, v57, v111, s[38:39]
	v_cndmask_b32_e64 v57, v121, v105, s[40:41]
	v_cndmask_b32_e64 v56, v125, v127, s[40:41]
	v_cndmask_b32_e64 v42, v115, v123, s[38:39]
	v_pk_fma_f32 v[56:57], v[62:63], v[56:57], v[74:75]
	s_nop 0
	v_pk_fma_f32 v[42:43], v[58:59], v[42:43], v[56:57]
	s_nop 0
	v_pk_fma_f32 v[42:43], v[82:83], v[50:51], v[42:43]
	s_nop 0
	v_mul_f32_e32 v50, 0xbfb8aa3b, v43
	v_exp_f32_e32 v50, v50
	s_nop 0
	v_add_f32_e32 v50, 1.0, v50
	v_rcp_f32_e32 v50, v50
	s_nop 0
	v_mul_f32_e32 v43, v43, v50
	v_mul_f32_e32 v62, v42, v43
	global_load_dword v51, v[6:7], off offset:12
	global_load_dword v43, v[8:9], off offset:2060
	global_load_dword v42, v[10:11], off offset:12
	global_load_dword v57, v[16:17], off offset:12
	global_load_dword v56, v[20:21], off offset:3084
	global_load_dword v50, v[18:19], off offset:3084
	global_load_dword v75, v[22:23], off offset:1036
	global_load_dword v74, v[24:25], off offset:3084
	v_mov_b32_dpp v105, v154 row_ror:1 row_mask:0xf bank_mask:0xf
	v_mov_b32_dpp v111, v154 row_ror:2 row_mask:0xf bank_mask:0xf
	v_cndmask_b32_e64 v155, v105, 0, s[38:39]
	v_cndmask_b32_e64 v58, 0, v111, s[40:41]
	v_mov_b32_dpp v115, v158 row_ror:1 row_mask:0xf bank_mask:0xf
	v_cndmask_b32_e64 v159, v115, 0, s[38:39]
	v_mov_b32_dpp v121, v158 row_ror:2 row_mask:0xf bank_mask:0xf
	v_cndmask_b32_e64 v63, 0, v121, s[40:41]
	s_waitcnt vmcnt(4)
; __device__ __forceinline__ float sigmoidf_(float x) { return __builtin_amdgcn_rcpf(1.0f + __expf(-x)); }
; template <int N> __device__ __forceinline__ float dpp_ror(float v) { return __builtin_bit_cast(float, __builtin_amdgcn_update_dpp(0, __builtin_bit_cast(int, v), 0x120 + N, 0xf, 0xf, false)); }
;     __device__ __forceinline__ void operator()(Acc& acc, const Unit& u, int wr, int wc, int fr, int fq) const {
;     ...
;             for (int i = 0; i < 4; ++i) {
;                 const int cg_ = ch0 + 4 * n + i, cv_ = DFF + cg_;
;                 const float g0 = cw[cg_], g1 = cw[NUP + cg_], g2 = cw[2 * NUP + cg_], gb = cb[cg_];
;                 const float v0 = cw[cv_], v1 = cw[NUP + cv_], v2 = cw[2 * NUP + cv_], vb = cb[cv_];
;                 float pg1 = 0.f, pg2 = 0.f, pv1 = 0.f, pv2 = 0.f;
; #pragma unroll
;                 for (int q = 0; q < 8; ++q) {
;                     float cgv = acc[q >> 2][0][q & 3][n][i], cvv = acc[q >> 2][1][q & 3][n][i];
;                     asm volatile("" : "+v"(cgv), "+v"(cvv) : "v"(chain));
;                     const float tg1 = dpp_ror<1>(cgv), tg2 = dpp_ror<2>(cgv), tv1 = dpp_ror<1>(cvv), tv2 = dpp_ror<2>(cvv);
;                     const float sg1 = fr >= 1 ? tg1 : pg1, sg2 = fr >= 2 ? tg2 : pg2, sv1 = fr >= 1 ? tv1 : pv1, sv2 = fr >= 2 ? tv2 : pv2;
;                     const float gg = gb + g0 * sg2 + g1 * sg1 + g2 * cgv;
;                     const float vv = vb + v0 * sv2 + v1 * sv1 + v2 * cvv;
;                     chain = gg * sigmoidf_(gg) * vv; acc[q >> 2][0][q & 3][n][i] = chain;
;                     pg1 = tg1; pg2 = tg2; pv1 = tv1; pv2 = tv2;
;                 }
	v_fma_f32 v82, v51, v58, v57
	v_pk_mul_f32 v[58:59], v[42:43], v[154:155]
	s_waitcnt vmcnt(2)
	v_fma_f32 v63, v50, v63, v56
	v_add_f32_e32 v59, v59, v82
	v_add_f32_e32 v131, v58, v59
	v_mul_f32_e32 v58, 0xbfb8aa3b, v131
	v_exp_f32_e32 v132, v58
	v_mov_b32_e32 v59, v42
	s_waitcnt vmcnt(0)
	v_pk_mul_f32 v[82:83], v[74:75], v[158:159]
	v_mov_b32_e32 v58, v74
	v_add_f32_e32 v42, 1.0, v132
	v_rcp_f32_e32 v74, v42
	v_add_f32_e32 v63, v83, v63
	v_add_f32_e32 v63, v82, v63
	v_mov_b32_e32 v42, v75
	v_mul_f32_e32 v74, v131, v74
	v_mul_f32_e32 v63, v63, v74
	v_mov_b32_dpp v125, v157 row_ror:2 row_mask:0xf bank_mask:0xf
	v_mov_b32_dpp v129, v156 row_ror:2 row_mask:0xf bank_mask:0xf
	v_mov_b32_dpp v123, v157 row_ror:1 row_mask:0xf bank_mask:0xf
	v_mov_b32_dpp v127, v156 row_ror:1 row_mask:0xf bank_mask:0xf
	v_cndmask_b32_e64 v83, v111, v125, s[40:41]
	v_cndmask_b32_e64 v82, v121, v129, s[40:41]
	v_cndmask_b32_e64 v75, v123, v105, s[38:39]
	v_cndmask_b32_e64 v74, v127, v115, s[38:39]
	v_pk_fma_f32 v[82:83], v[50:51], v[82:83], v[56:57]
	v_pk_fma_f32 v[74:75], v[42:43], v[74:75], v[82:83]
	v_pk_fma_f32 v[74:75], v[58:59], v[156:157], v[74:75]
	v_mul_f32_e32 v82, 0xbfb8aa3b, v75
	v_exp_f32_e32 v82, v82
	s_nop 0
	v_add_f32_e32 v82, 1.0, v82
	v_rcp_f32_e32 v82, v82
	s_nop 0
	v_mul_f32_e32 v75, v75, v82
	v_mul_f32_e32 v74, v74, v75
	v_mov_b32_dpp v111, v103 row_ror:2 row_mask:0xf bank_mask:0xf
	v_mov_b32_dpp v121, v102 row_ror:2 row_mask:0xf bank_mask:0xf
	v_mov_b32_dpp v105, v103 row_ror:1 row_mask:0xf bank_mask:0xf
	v_mov_b32_dpp v115, v102 row_ror:1 row_mask:0xf bank_mask:0xf
	v_cndmask_b32_e64 v133, v125, v111, s[40:41]
	v_cndmask_b32_e64 v132, v129, v121, s[40:41]
	v_cndmask_b32_e64 v83, v105, v123, s[38:39]
	v_cndmask_b32_e64 v82, v115, v127, s[38:39]
	v_pk_fma_f32 v[132:133], v[50:51], v[132:133], v[56:57]
	v_pk_fma_f32 v[82:83], v[42:43], v[82:83], v[132:133]
	v_pk_fma_f32 v[82:83], v[58:59], v[102:103], v[82:83]
	v_mul_f32_e32 v75, 0xbfb8aa3b, v83
	v_exp_f32_e32 v75, v75
	s_nop 0
	v_add_f32_e32 v75, 1.0, v75
	v_rcp_f32_e32 v75, v75
	s_nop 0
	v_mul_f32_e32 v75, v83, v75
	v_mul_f32_e32 v75, v82, v75
	v_mov_b32_dpp v125, v87 row_ror:2 row_mask:0xf bank_mask:0xf
	v_mov_b32_dpp v129, v86 row_ror:2 row_mask:0xf bank_mask:0xf
	v_mov_b32_dpp v123, v87 row_ror:1 row_mask:0xf bank_mask:0xf
	v_mov_b32_dpp v127, v86 row_ror:1 row_mask:0xf bank_mask:0xf
	v_cndmask_b32_e64 v103, v111, v125, s[40:41]
	v_cndmask_b32_e64 v102, v121, v129, s[40:41]
	v_cndmask_b32_e64 v83, v123, v105, s[38:39]
	v_cndmask_b32_e64 v82, v127, v115, s[38:39]
	v_pk_fma_f32 v[102:103], v[50:51], v[102:103], v[56:57]
	v_pk_fma_f32 v[82:83], v[42:43], v[82:83], v[102:103]
	v_pk_fma_f32 v[82:83], v[58:59], v[86:87], v[82:83]
	v_mul_f32_e32 v86, 0xbfb8aa3b, v83
	v_exp_f32_e32 v86, v86
	s_nop 0
	v_add_f32_e32 v86, 1.0, v86
	v_rcp_f32_e32 v86, v86
	s_nop 0
	v_mul_f32_e32 v83, v83, v86
	v_mul_f32_e32 v82, v82, v83
	v_mov_b32_dpp v111, v71 row_ror:2 row_mask:0xf bank_mask:0xf
	v_mov_b32_dpp v121, v70 row_ror:2 row_mask:0xf bank_mask:0xf
	v_mov_b32_dpp v105, v71 row_ror:1 row_mask:0xf bank_mask:0xf
	v_mov_b32_dpp v115, v70 row_ror:1 row_mask:0xf bank_mask:0xf
	v_cndmask_b32_e64 v103, v125, v111, s[40:41]
	v_cndmask_b32_e64 v102, v129, v121, s[40:41]
	v_cndmask_b32_e64 v87, v105, v123, s[38:39]
	v_cndmask_b32_e64 v86, v115, v127, s[38:39]
	v_pk_fma_f32 v[102:103], v[50:51], v[102:103], v[56:57]
	v_pk_fma_f32 v[86:87], v[42:43], v[86:87], v[102:103]
	v_pk_fma_f32 v[70:71], v[58:59], v[70:71], v[86:87]
	v_mul_f32_e32 v83, 0xbfb8aa3b, v71
	v_exp_f32_e32 v83, v83
	s_nop 0
	v_add_f32_e32 v83, 1.0, v83
	v_rcp_f32_e32 v83, v83
	s_nop 0
	v_mul_f32_e32 v71, v71, v83
	v_mul_f32_e32 v70, v70, v71
	v_mov_b32_dpp v125, v55 row_ror:2 row_mask:0xf bank_mask:0xf
	v_mov_b32_dpp v129, v54 row_ror:2 row_mask:0xf bank_mask:0xf
	v_mov_b32_dpp v123, v55 row_ror:1 row_mask:0xf bank_mask:0xf
	v_mov_b32_dpp v127, v54 row_ror:1 row_mask:0xf bank_mask:0xf
	v_cndmask_b32_e64 v103, v111, v125, s[40:41]
	v_cndmask_b32_e64 v102, v121, v129, s[40:41]
	v_cndmask_b32_e64 v87, v123, v105, s[38:39]
	v_cndmask_b32_e64 v86, v127, v115, s[38:39]
	v_pk_fma_f32 v[102:103], v[50:51], v[102:103], v[56:57]
	v_pk_fma_f32 v[86:87], v[42:43], v[86:87], v[102:103]
	v_pk_fma_f32 v[54:55], v[58:59], v[54:55], v[86:87]
	v_mul_f32_e32 v71, 0xbfb8aa3b, v55
	v_exp_f32_e32 v71, v71
	s_nop 0
	v_add_f32_e32 v71, 1.0, v71
	v_rcp_f32_e32 v71, v71
	s_nop 0
	v_mul_f32_e32 v55, v55, v71
	v_mul_f32_e32 v55, v54, v55
	v_mov_b32_dpp v105, v39 row_ror:2 row_mask:0xf bank_mask:0xf
	v_mov_b32_dpp v115, v38 row_ror:2 row_mask:0xf bank_mask:0xf
	v_mov_b32_dpp v83, v39 row_ror:1 row_mask:0xf bank_mask:0xf
	v_mov_b32_dpp v111, v38 row_ror:1 row_mask:0xf bank_mask:0xf
	v_cndmask_b32_e64 v103, v125, v105, s[40:41]
	v_cndmask_b32_e64 v102, v129, v115, s[40:41]
	v_cndmask_b32_e64 v87, v83, v123, s[38:39]
	v_cndmask_b32_e64 v86, v111, v127, s[38:39]
	v_pk_fma_f32 v[102:103], v[50:51], v[102:103], v[56:57]
	s_nop 0
	v_pk_fma_f32 v[86:87], v[42:43], v[86:87], v[102:103]
	v_pk_fma_f32 v[38:39], v[58:59], v[38:39], v[86:87]
	v_mul_f32_e32 v54, 0xbfb8aa3b, v39
	v_exp_f32_e32 v54, v54
	s_nop 0
	v_add_f32_e32 v54, 1.0, v54
	v_rcp_f32_e32 v54, v54
	s_nop 0
	v_mul_f32_e32 v39, v39, v54
	v_mul_f32_e32 v71, v38, v39
	v_mov_b32_dpp v86, v41 row_ror:1 row_mask:0xf bank_mask:0xf
	v_mov_b32_dpp v87, v41 row_ror:2 row_mask:0xf bank_mask:0xf
	v_mov_b32_dpp v103, v40 row_ror:2 row_mask:0xf bank_mask:0xf
	v_mov_b32_dpp v102, v40 row_ror:1 row_mask:0xf bank_mask:0xf
	v_cndmask_b32_e64 v39, v86, v83, s[38:39]
	v_cndmask_b32_e64 v87, v105, v87, s[40:41]
	v_cndmask_b32_e64 v86, v115, v103, s[40:41]
	v_cndmask_b32_e64 v38, v102, v111, s[38:39]
	v_pk_fma_f32 v[50:51], v[50:51], v[86:87], v[56:57]
	s_nop 0
	v_pk_fma_f32 v[38:39], v[42:43], v[38:39], v[50:51]
	s_nop 0
	v_pk_fma_f32 v[38:39], v[58:59], v[40:41], v[38:39]
	s_nop 0
	v_mul_f32_e32 v40, 0xbfb8aa3b, v39
	v_exp_f32_e32 v40, v40
	s_nop 0
	v_add_f32_e32 v40, 1.0, v40
	v_rcp_f32_e32 v40, v40
	s_nop 0
	v_mul_f32_e32 v39, v39, v40
	v_mul_f32_e32 v54, v38, v39
	global_load_dword v41, v[6:7], off offset:16
	global_load_dword v39, v[8:9], off offset:2064
	global_load_dword v38, v[10:11], off offset:16
	global_load_dword v43, v[16:17], off offset:16
	global_load_dword v42, v[20:21], off offset:3088
	global_load_dword v40, v[18:19], off offset:3088
	global_load_dword v57, v[22:23], off offset:1040
	global_load_dword v56, v[24:25], off offset:3088
	v_mov_b32_dpp v83, v130 row_ror:1 row_mask:0xf bank_mask:0xf
	v_mov_b32_dpp v86, v130 row_ror:2 row_mask:0xf bank_mask:0xf
	v_cndmask_b32_e64 v131, v83, 0, s[38:39]
	v_cndmask_b32_e64 v50, 0, v86, s[40:41]
	v_mov_b32_dpp v87, v152 row_ror:1 row_mask:0xf bank_mask:0xf
	v_mov_b32_dpp v102, v152 row_ror:2 row_mask:0xf bank_mask:0xf
	v_cndmask_b32_e64 v153, v87, 0, s[38:39]
	v_cndmask_b32_e64 v58, 0, v102, s[40:41]
	s_waitcnt vmcnt(4)
; __device__ __forceinline__ float sigmoidf_(float x) { return __builtin_amdgcn_rcpf(1.0f + __expf(-x)); }
; template <int N> __device__ __forceinline__ float dpp_ror(float v) { return __builtin_bit_cast(float, __builtin_amdgcn_update_dpp(0, __builtin_bit_cast(int, v), 0x120 + N, 0xf, 0xf, false)); }
;     __device__ __forceinline__ void operator()(Acc& acc, const Unit& u, int wr, int wc, int fr, int fq) const {
;     ...
;             for (int i = 0; i < 4; ++i) {
;                 const int cg_ = ch0 + 4 * n + i, cv_ = DFF + cg_;
;                 const float g0 = cw[cg_], g1 = cw[NUP + cg_], g2 = cw[2 * NUP + cg_], gb = cb[cg_];
;                 const float v0 = cw[cv_], v1 = cw[NUP + cv_], v2 = cw[2 * NUP + cv_], vb = cb[cv_];
;                 float pg1 = 0.f, pg2 = 0.f, pv1 = 0.f, pv2 = 0.f;
; #pragma unroll
;                 for (int q = 0; q < 8; ++q) {
;                     float cgv = acc[q >> 2][0][q & 3][n][i], cvv = acc[q >> 2][1][q & 3][n][i];
;                     asm volatile("" : "+v"(cgv), "+v"(cvv) : "v"(chain));
;                     const float tg1 = dpp_ror<1>(cgv), tg2 = dpp_ror<2>(cgv), tv1 = dpp_ror<1>(cvv), tv2 = dpp_ror<2>(cvv);
;                     const float sg1 = fr >= 1 ? tg1 : pg1, sg2 = fr >= 2 ? tg2 : pg2, sv1 = fr >= 1 ? tv1 : pv1, sv2 = fr >= 2 ? tv2 : pv2;
;                     const float gg = gb + g0 * sg2 + g1 * sg1 + g2 * cgv;
;                     const float vv = vb + v0 * sv2 + v1 * sv1 + v2 * cvv;
;                     chain = gg * sigmoidf_(gg) * vv; acc[q >> 2][0][q & 3][n][i] = chain;
;                     pg1 = tg1; pg2 = tg2; pv1 = tv1; pv2 = tv2;
;                 }
	v_fma_f32 v59, v41, v50, v43
	v_pk_mul_f32 v[50:51], v[38:39], v[130:131]
	s_waitcnt vmcnt(2)
	v_fma_f32 v121, v40, v58, v42
	v_add_f32_e32 v51, v51, v59
	v_add_f32_e32 v123, v50, v51
	v_mul_f32_e32 v50, 0xbfb8aa3b, v123
	v_exp_f32_e32 v125, v50
	v_mov_b32_e32 v51, v38
	s_waitcnt vmcnt(0)
	v_pk_mul_f32 v[58:59], v[56:57], v[152:153]
	v_mov_b32_e32 v50, v56
	v_add_f32_e32 v38, 1.0, v125
	v_rcp_f32_e32 v56, v38
	v_mov_b32_e32 v38, v57
	v_add_f32_e32 v57, v59, v121
	v_add_f32_e32 v57, v58, v57
	v_mul_f32_e32 v56, v123, v56
	v_mul_f32_e32 v56, v57, v56
	v_mov_b32_dpp v105, v119 row_ror:2 row_mask:0xf bank_mask:0xf
	v_mov_b32_dpp v111, v118 row_ror:1 row_mask:0xf bank_mask:0xf
	v_mov_b32_dpp v115, v118 row_ror:2 row_mask:0xf bank_mask:0xf
	v_mov_b32_dpp v103, v119 row_ror:1 row_mask:0xf bank_mask:0xf
	v_cndmask_b32_e64 v58, v111, v87, s[38:39]
	v_cndmask_b32_e64 v87, v86, v105, s[40:41]
	v_cndmask_b32_e64 v86, v102, v115, s[40:41]
	v_cndmask_b32_e64 v59, v103, v83, s[38:39]
	v_pk_fma_f32 v[86:87], v[40:41], v[86:87], v[42:43]
	v_pk_fma_f32 v[58:59], v[38:39], v[58:59], v[86:87]
	v_pk_fma_f32 v[58:59], v[50:51], v[118:119], v[58:59]
	v_mul_f32_e32 v57, 0xbfb8aa3b, v59
	v_exp_f32_e32 v57, v57
	s_nop 0
	v_add_f32_e32 v57, 1.0, v57
	v_rcp_f32_e32 v57, v57
	s_nop 0
	v_mul_f32_e32 v57, v59, v57
	v_mul_f32_e32 v57, v58, v57
	v_mov_b32_dpp v102, v101 row_ror:2 row_mask:0xf bank_mask:0xf
	v_mov_b32_dpp v119, v100 row_ror:2 row_mask:0xf bank_mask:0xf
	v_mov_b32_dpp v83, v101 row_ror:1 row_mask:0xf bank_mask:0xf
	v_mov_b32_dpp v118, v100 row_ror:1 row_mask:0xf bank_mask:0xf
	v_cndmask_b32_e64 v87, v105, v102, s[40:41]
	v_cndmask_b32_e64 v86, v115, v119, s[40:41]
	v_cndmask_b32_e64 v59, v83, v103, s[38:39]
	v_cndmask_b32_e64 v58, v118, v111, s[38:39]
	v_pk_fma_f32 v[86:87], v[40:41], v[86:87], v[42:43]
	v_pk_fma_f32 v[58:59], v[38:39], v[58:59], v[86:87]
	v_pk_fma_f32 v[58:59], v[50:51], v[100:101], v[58:59]
	v_mul_f32_e32 v86, 0xbfb8aa3b, v59
	v_exp_f32_e32 v86, v86
	s_nop 0
	v_add_f32_e32 v86, 1.0, v86
	v_rcp_f32_e32 v86, v86
	s_nop 0
	v_mul_f32_e32 v59, v59, v86
	v_mul_f32_e32 v58, v58, v59
	v_mov_b32_dpp v105, v85 row_ror:2 row_mask:0xf bank_mask:0xf
	v_mov_b32_dpp v115, v84 row_ror:2 row_mask:0xf bank_mask:0xf
	v_mov_b32_dpp v103, v85 row_ror:1 row_mask:0xf bank_mask:0xf
	v_mov_b32_dpp v111, v84 row_ror:1 row_mask:0xf bank_mask:0xf
	v_cndmask_b32_e64 v101, v102, v105, s[40:41]
	v_cndmask_b32_e64 v100, v119, v115, s[40:41]
	v_cndmask_b32_e64 v87, v103, v83, s[38:39]
	v_cndmask_b32_e64 v86, v111, v118, s[38:39]
	v_pk_fma_f32 v[100:101], v[40:41], v[100:101], v[42:43]
	v_pk_fma_f32 v[86:87], v[38:39], v[86:87], v[100:101]
	v_pk_fma_f32 v[84:85], v[50:51], v[84:85], v[86:87]
	v_mul_f32_e32 v59, 0xbfb8aa3b, v85
	v_exp_f32_e32 v59, v59
	s_nop 0
	v_add_f32_e32 v59, 1.0, v59
	v_rcp_f32_e32 v59, v59
	s_nop 0
	v_mul_f32_e32 v59, v85, v59
	v_mul_f32_e32 v59, v84, v59
	v_mov_b32_dpp v100, v69 row_ror:2 row_mask:0xf bank_mask:0xf
	v_mov_b32_dpp v102, v68 row_ror:2 row_mask:0xf bank_mask:0xf
	v_mov_b32_dpp v83, v69 row_ror:1 row_mask:0xf bank_mask:0xf
	v_mov_b32_dpp v101, v68 row_ror:1 row_mask:0xf bank_mask:0xf
	v_cndmask_b32_e64 v87, v105, v100, s[40:41]
	v_cndmask_b32_e64 v86, v115, v102, s[40:41]
	v_cndmask_b32_e64 v85, v83, v103, s[38:39]
	v_cndmask_b32_e64 v84, v101, v111, s[38:39]
	v_pk_fma_f32 v[86:87], v[40:41], v[86:87], v[42:43]
	v_pk_fma_f32 v[84:85], v[38:39], v[84:85], v[86:87]
	v_pk_fma_f32 v[68:69], v[50:51], v[68:69], v[84:85]
	v_mul_f32_e32 v84, 0xbfb8aa3b, v69
	v_exp_f32_e32 v84, v84
	s_nop 0
	v_add_f32_e32 v84, 1.0, v84
	v_rcp_f32_e32 v84, v84
	s_nop 0
	v_mul_f32_e32 v69, v69, v84
	v_mul_f32_e32 v68, v68, v69
	v_mov_b32_dpp v105, v53 row_ror:2 row_mask:0xf bank_mask:0xf
	v_mov_b32_dpp v115, v52 row_ror:2 row_mask:0xf bank_mask:0xf
	v_mov_b32_dpp v103, v53 row_ror:1 row_mask:0xf bank_mask:0xf
	v_mov_b32_dpp v111, v52 row_ror:1 row_mask:0xf bank_mask:0xf
	v_cndmask_b32_e64 v87, v100, v105, s[40:41]
	v_cndmask_b32_e64 v86, v102, v115, s[40:41]
	v_cndmask_b32_e64 v85, v103, v83, s[38:39]
	v_cndmask_b32_e64 v84, v111, v101, s[38:39]
	v_pk_fma_f32 v[86:87], v[40:41], v[86:87], v[42:43]
	v_pk_fma_f32 v[84:85], v[38:39], v[84:85], v[86:87]
	v_pk_fma_f32 v[52:53], v[50:51], v[52:53], v[84:85]
	v_mul_f32_e32 v69, 0xbfb8aa3b, v53
	v_exp_f32_e32 v69, v69
	s_nop 0
	v_add_f32_e32 v69, 1.0, v69
	v_rcp_f32_e32 v69, v69
	s_nop 0
	v_mul_f32_e32 v53, v53, v69
	v_mul_f32_e32 v52, v52, v53
	v_mov_b32_dpp v100, v37 row_ror:2 row_mask:0xf bank_mask:0xf
	v_mov_b32_dpp v102, v36 row_ror:2 row_mask:0xf bank_mask:0xf
	v_mov_b32_dpp v83, v37 row_ror:1 row_mask:0xf bank_mask:0xf
	v_mov_b32_dpp v101, v36 row_ror:1 row_mask:0xf bank_mask:0xf
	v_cndmask_b32_e64 v87, v105, v100, s[40:41]
	v_cndmask_b32_e64 v86, v115, v102, s[40:41]
	v_cndmask_b32_e64 v85, v83, v103, s[38:39]
	v_cndmask_b32_e64 v84, v101, v111, s[38:39]
	v_pk_fma_f32 v[86:87], v[40:41], v[86:87], v[42:43]
	s_nop 0
	v_pk_fma_f32 v[84:85], v[38:39], v[84:85], v[86:87]
	v_pk_fma_f32 v[36:37], v[50:51], v[36:37], v[84:85]
	v_mul_f32_e32 v53, 0xbfb8aa3b, v37
	v_exp_f32_e32 v53, v53
	s_nop 0
	v_add_f32_e32 v53, 1.0, v53
	v_rcp_f32_e32 v53, v53
	s_nop 0
	v_mul_f32_e32 v37, v37, v53
	v_mul_f32_e32 v53, v36, v37
	v_mov_b32_dpp v84, v35 row_ror:2 row_mask:0xf bank_mask:0xf
	v_mov_b32_dpp v85, v34 row_ror:1 row_mask:0xf bank_mask:0xf
	v_mov_b32_dpp v86, v34 row_ror:2 row_mask:0xf bank_mask:0xf
	v_mov_b32_dpp v69, v35 row_ror:1 row_mask:0xf bank_mask:0xf
	v_cndmask_b32_e64 v36, v85, v101, s[38:39]
	v_cndmask_b32_e64 v85, v100, v84, s[40:41]
	v_cndmask_b32_e64 v84, v102, v86, s[40:41]
	v_cndmask_b32_e64 v37, v69, v83, s[38:39]
	v_pk_fma_f32 v[40:41], v[40:41], v[84:85], v[42:43]
	s_nop 0
	v_pk_fma_f32 v[36:37], v[38:39], v[36:37], v[40:41]
	s_nop 0
	v_pk_fma_f32 v[34:35], v[50:51], v[34:35], v[36:37]
	s_nop 0
	v_mul_f32_e32 v36, 0xbfb8aa3b, v35
	v_exp_f32_e32 v36, v36
	s_nop 0
	v_add_f32_e32 v36, 1.0, v36
	v_rcp_f32_e32 v36, v36
	s_nop 0
	v_mul_f32_e32 v35, v35, v36
	v_mul_f32_e32 v42, v34, v35
	global_load_dword v37, v[6:7], off offset:20
	global_load_dword v35, v[8:9], off offset:2068
	global_load_dword v34, v[10:11], off offset:20
	global_load_dword v39, v[16:17], off offset:20
	global_load_dword v38, v[20:21], off offset:3092
	global_load_dword v36, v[18:19], off offset:3092
	global_load_dword v51, v[22:23], off offset:1044
	global_load_dword v50, v[24:25], off offset:3092
	v_mov_b32_dpp v69, v126 row_ror:1 row_mask:0xf bank_mask:0xf
	v_mov_b32_dpp v83, v126 row_ror:2 row_mask:0xf bank_mask:0xf
	v_cndmask_b32_e64 v127, v69, 0, s[38:39]
	v_cndmask_b32_e64 v40, 0, v83, s[40:41]
	v_mov_b32_dpp v86, v128 row_ror:1 row_mask:0xf bank_mask:0xf
	v_cndmask_b32_e64 v129, v86, 0, s[38:39]
	v_mov_b32_dpp v87, v128 row_ror:2 row_mask:0xf bank_mask:0xf
	v_cndmask_b32_e64 v43, 0, v87, s[40:41]
	s_waitcnt vmcnt(4)
; __device__ __forceinline__ float sigmoidf_(float x) { return __builtin_amdgcn_rcpf(1.0f + __expf(-x)); }
; template <int N> __device__ __forceinline__ float dpp_ror(float v) { return __builtin_bit_cast(float, __builtin_amdgcn_update_dpp(0, __builtin_bit_cast(int, v), 0x120 + N, 0xf, 0xf, false)); }
;     __device__ __forceinline__ void operator()(Acc& acc, const Unit& u, int wr, int wc, int fr, int fq) const {
;     ...
;             for (int i = 0; i < 4; ++i) {
;                 const int cg_ = ch0 + 4 * n + i, cv_ = DFF + cg_;
;                 const float g0 = cw[cg_], g1 = cw[NUP + cg_], g2 = cw[2 * NUP + cg_], gb = cb[cg_];
;                 const float v0 = cw[cv_], v1 = cw[NUP + cv_], v2 = cw[2 * NUP + cv_], vb = cb[cv_];
;                 float pg1 = 0.f, pg2 = 0.f, pv1 = 0.f, pv2 = 0.f;
; #pragma unroll
;                 for (int q = 0; q < 8; ++q) {
;                     float cgv = acc[q >> 2][0][q & 3][n][i], cvv = acc[q >> 2][1][q & 3][n][i];
;                     asm volatile("" : "+v"(cgv), "+v"(cvv) : "v"(chain));
;                     const float tg1 = dpp_ror<1>(cgv), tg2 = dpp_ror<2>(cgv), tv1 = dpp_ror<1>(cvv), tv2 = dpp_ror<2>(cvv);
;                     const float sg1 = fr >= 1 ? tg1 : pg1, sg2 = fr >= 2 ? tg2 : pg2, sv1 = fr >= 1 ? tv1 : pv1, sv2 = fr >= 2 ? tv2 : pv2;
;                     const float gg = gb + g0 * sg2 + g1 * sg1 + g2 * cgv;
;                     const float vv = vb + v0 * sv2 + v1 * sv1 + v2 * cvv;
;                     chain = gg * sigmoidf_(gg) * vv; acc[q >> 2][0][q & 3][n][i] = chain;
;                     pg1 = tg1; pg2 = tg2; pv1 = tv1; pv2 = tv2;
;                 }
	v_fma_f32 v84, v37, v40, v39
	v_pk_mul_f32 v[40:41], v[34:35], v[126:127]
	s_waitcnt vmcnt(2)
	v_fma_f32 v43, v36, v43, v38
	v_add_f32_e32 v41, v41, v84
	v_add_f32_e32 v105, v40, v41
	v_mul_f32_e32 v40, 0xbfb8aa3b, v105
	v_exp_f32_e32 v111, v40
	v_mov_b32_e32 v41, v34
	s_waitcnt vmcnt(0)
	v_pk_mul_f32 v[84:85], v[50:51], v[128:129]
	v_mov_b32_e32 v40, v50
	v_add_f32_e32 v34, 1.0, v111
	v_rcp_f32_e32 v50, v34
	v_add_f32_e32 v43, v85, v43
	v_add_f32_e32 v43, v84, v43
	v_mov_b32_e32 v34, v51
	v_mul_f32_e32 v50, v105, v50
	v_mul_f32_e32 v43, v43, v50
	v_mov_b32_dpp v101, v117 row_ror:2 row_mask:0xf bank_mask:0xf
	v_mov_b32_dpp v103, v116 row_ror:2 row_mask:0xf bank_mask:0xf
	v_mov_b32_dpp v100, v117 row_ror:1 row_mask:0xf bank_mask:0xf
	v_mov_b32_dpp v102, v116 row_ror:1 row_mask:0xf bank_mask:0xf
	v_cndmask_b32_e64 v85, v83, v101, s[40:41]
	v_cndmask_b32_e64 v84, v87, v103, s[40:41]
	v_cndmask_b32_e64 v51, v100, v69, s[38:39]
	v_cndmask_b32_e64 v50, v102, v86, s[38:39]
	v_pk_fma_f32 v[84:85], v[36:37], v[84:85], v[38:39]
	v_pk_fma_f32 v[50:51], v[34:35], v[50:51], v[84:85]
	s_nop 0
	v_pk_fma_f32 v[50:51], v[40:41], v[116:117], v[50:51]
	s_nop 0
	v_mul_f32_e32 v69, 0xbfb8aa3b, v51
	v_exp_f32_e32 v69, v69
	s_nop 0
	v_add_f32_e32 v69, 1.0, v69
	v_rcp_f32_e32 v69, v69
	s_nop 0
	v_mul_f32_e32 v51, v51, v69
	v_mul_f32_e32 v50, v50, v51
	v_mov_b32_dpp v105, v97 row_ror:2 row_mask:0xf bank_mask:0xf
	v_mov_b32_dpp v115, v96 row_ror:2 row_mask:0xf bank_mask:0xf
	v_mov_b32_dpp v83, v97 row_ror:1 row_mask:0xf bank_mask:0xf
	v_mov_b32_dpp v111, v96 row_ror:1 row_mask:0xf bank_mask:0xf
	v_cndmask_b32_e64 v87, v101, v105, s[40:41]
	v_cndmask_b32_e64 v86, v103, v115, s[40:41]
	v_cndmask_b32_e64 v85, v83, v100, s[38:39]
	v_cndmask_b32_e64 v84, v111, v102, s[38:39]
	v_pk_fma_f32 v[86:87], v[36:37], v[86:87], v[38:39]
	v_pk_fma_f32 v[84:85], v[34:35], v[84:85], v[86:87]
	v_pk_fma_f32 v[84:85], v[40:41], v[96:97], v[84:85]
	v_mul_f32_e32 v51, 0xbfb8aa3b, v85
	v_exp_f32_e32 v51, v51
	s_nop 0
	v_add_f32_e32 v51, 1.0, v51
	v_rcp_f32_e32 v51, v51
	s_nop 0
	v_mul_f32_e32 v51, v85, v51
	v_mul_f32_e32 v51, v84, v51
	v_mov_b32_dpp v97, v81 row_ror:2 row_mask:0xf bank_mask:0xf
	v_mov_b32_dpp v101, v80 row_ror:2 row_mask:0xf bank_mask:0xf
	v_mov_b32_dpp v96, v81 row_ror:1 row_mask:0xf bank_mask:0xf
	v_mov_b32_dpp v100, v80 row_ror:1 row_mask:0xf bank_mask:0xf
	v_cndmask_b32_e64 v87, v105, v97, s[40:41]
	v_cndmask_b32_e64 v86, v115, v101, s[40:41]
	v_cndmask_b32_e64 v85, v96, v83, s[38:39]
	v_cndmask_b32_e64 v84, v100, v111, s[38:39]
	v_pk_fma_f32 v[86:87], v[36:37], v[86:87], v[38:39]
	v_pk_fma_f32 v[84:85], v[34:35], v[84:85], v[86:87]
	v_pk_fma_f32 v[80:81], v[40:41], v[80:81], v[84:85]
	v_mul_f32_e32 v69, 0xbfb8aa3b, v81
	v_exp_f32_e32 v69, v69
	s_nop 0
	v_add_f32_e32 v69, 1.0, v69
	v_rcp_f32_e32 v69, v69
	s_nop 0
	v_mul_f32_e32 v69, v81, v69
	v_mul_f32_e32 v69, v80, v69
	v_mov_b32_dpp v86, v67 row_ror:2 row_mask:0xf bank_mask:0xf
	v_mov_b32_dpp v102, v66 row_ror:2 row_mask:0xf bank_mask:0xf
	v_mov_b32_dpp v83, v67 row_ror:1 row_mask:0xf bank_mask:0xf
	v_mov_b32_dpp v87, v66 row_ror:1 row_mask:0xf bank_mask:0xf
	v_cndmask_b32_e64 v85, v97, v86, s[40:41]
	v_cndmask_b32_e64 v84, v101, v102, s[40:41]
	v_cndmask_b32_e64 v81, v83, v96, s[38:39]
	v_cndmask_b32_e64 v80, v87, v100, s[38:39]
	v_pk_fma_f32 v[84:85], v[36:37], v[84:85], v[38:39]
	v_pk_fma_f32 v[80:81], v[34:35], v[80:81], v[84:85]
	v_pk_fma_f32 v[66:67], v[40:41], v[66:67], v[80:81]
	v_mul_f32_e32 v80, 0xbfb8aa3b, v67
	v_exp_f32_e32 v80, v80
	s_nop 0
	v_add_f32_e32 v80, 1.0, v80
	v_rcp_f32_e32 v80, v80
	s_nop 0
	v_mul_f32_e32 v67, v67, v80
	v_mul_f32_e32 v66, v66, v67
	v_mov_b32_dpp v97, v49 row_ror:2 row_mask:0xf bank_mask:0xf
	v_mov_b32_dpp v101, v48 row_ror:2 row_mask:0xf bank_mask:0xf
	v_mov_b32_dpp v96, v49 row_ror:1 row_mask:0xf bank_mask:0xf
	v_mov_b32_dpp v100, v48 row_ror:1 row_mask:0xf bank_mask:0xf
	v_cndmask_b32_e64 v85, v86, v97, s[40:41]
	v_cndmask_b32_e64 v84, v102, v101, s[40:41]
	v_cndmask_b32_e64 v81, v96, v83, s[38:39]
	v_cndmask_b32_e64 v80, v100, v87, s[38:39]
	v_pk_fma_f32 v[84:85], v[36:37], v[84:85], v[38:39]
	v_pk_fma_f32 v[80:81], v[34:35], v[80:81], v[84:85]
	v_pk_fma_f32 v[48:49], v[40:41], v[48:49], v[80:81]
	v_mul_f32_e32 v67, 0xbfb8aa3b, v49
	v_exp_f32_e32 v67, v67
	s_nop 0
	v_add_f32_e32 v67, 1.0, v67
	v_rcp_f32_e32 v67, v67
	s_nop 0
	v_mul_f32_e32 v49, v49, v67
	v_mul_f32_e32 v48, v48, v49
	v_mov_b32_dpp v86, v33 row_ror:2 row_mask:0xf bank_mask:0xf
	v_mov_b32_dpp v102, v32 row_ror:2 row_mask:0xf bank_mask:0xf
	v_mov_b32_dpp v83, v33 row_ror:1 row_mask:0xf bank_mask:0xf
	v_mov_b32_dpp v87, v32 row_ror:1 row_mask:0xf bank_mask:0xf
	v_cndmask_b32_e64 v85, v97, v86, s[40:41]
	v_cndmask_b32_e64 v84, v101, v102, s[40:41]
	v_cndmask_b32_e64 v81, v83, v96, s[38:39]
	v_cndmask_b32_e64 v80, v87, v100, s[38:39]
	v_pk_fma_f32 v[84:85], v[36:37], v[84:85], v[38:39]
	s_nop 0
	v_pk_fma_f32 v[80:81], v[34:35], v[80:81], v[84:85]
	v_pk_fma_f32 v[32:33], v[40:41], v[32:33], v[80:81]
	v_mul_f32_e32 v49, 0xbfb8aa3b, v33
	v_exp_f32_e32 v49, v49
	s_nop 0
	v_add_f32_e32 v49, 1.0, v49
	v_rcp_f32_e32 v49, v49
	s_nop 0
	v_mul_f32_e32 v33, v33, v49
	v_mul_f32_e32 v49, v32, v33
	v_mov_b32_dpp v80, v27 row_ror:2 row_mask:0xf bank_mask:0xf
	v_mov_b32_dpp v81, v26 row_ror:1 row_mask:0xf bank_mask:0xf
	v_mov_b32_dpp v84, v26 row_ror:2 row_mask:0xf bank_mask:0xf
	v_mov_b32_dpp v67, v27 row_ror:1 row_mask:0xf bank_mask:0xf
	v_cndmask_b32_e64 v32, v81, v87, s[38:39]
	v_cndmask_b32_e64 v81, v86, v80, s[40:41]
	v_cndmask_b32_e64 v80, v102, v84, s[40:41]
	v_cndmask_b32_e64 v33, v67, v83, s[38:39]
	v_pk_fma_f32 v[36:37], v[36:37], v[80:81], v[38:39]
	s_nop 0
	v_pk_fma_f32 v[32:33], v[34:35], v[32:33], v[36:37]
	s_nop 0
	v_pk_fma_f32 v[26:27], v[40:41], v[26:27], v[32:33]
	s_nop 0
	v_mul_f32_e32 v32, 0xbfb8aa3b, v27
	v_exp_f32_e32 v32, v32
	s_nop 0
	v_add_f32_e32 v32, 1.0, v32
	v_rcp_f32_e32 v32, v32
	s_nop 0
	v_mul_f32_e32 v27, v27, v32
	v_mul_f32_e32 v38, v26, v27
	global_load_dword v33, v[6:7], off offset:24
	global_load_dword v27, v[8:9], off offset:2072
	global_load_dword v26, v[10:11], off offset:24
	global_load_dword v35, v[16:17], off offset:24
	global_load_dword v34, v[20:21], off offset:3096
	global_load_dword v32, v[18:19], off offset:3096
	global_load_dword v41, v[22:23], off offset:1048
	global_load_dword v40, v[24:25], off offset:3096
	v_mov_b32_dpp v67, v122 row_ror:1 row_mask:0xf bank_mask:0xf
	v_mov_b32_dpp v83, v122 row_ror:2 row_mask:0xf bank_mask:0xf
	v_cndmask_b32_e64 v123, v67, 0, s[38:39]
	v_cndmask_b32_e64 v36, 0, v83, s[40:41]
	v_mov_b32_dpp v84, v124 row_ror:1 row_mask:0xf bank_mask:0xf
	v_cndmask_b32_e64 v125, v84, 0, s[38:39]
	v_mov_b32_dpp v85, v124 row_ror:2 row_mask:0xf bank_mask:0xf
	v_cndmask_b32_e64 v39, 0, v85, s[40:41]
	s_waitcnt vmcnt(4)
; __device__ __forceinline__ float sigmoidf_(float x) { return __builtin_amdgcn_rcpf(1.0f + __expf(-x)); }
; template <int N> __device__ __forceinline__ float dpp_ror(float v) { return __builtin_bit_cast(float, __builtin_amdgcn_update_dpp(0, __builtin_bit_cast(int, v), 0x120 + N, 0xf, 0xf, false)); }
;     __device__ __forceinline__ void operator()(Acc& acc, const Unit& u, int wr, int wc, int fr, int fq) const {
;     ...
;             for (int i = 0; i < 4; ++i) {
;                 const int cg_ = ch0 + 4 * n + i, cv_ = DFF + cg_;
;                 const float g0 = cw[cg_], g1 = cw[NUP + cg_], g2 = cw[2 * NUP + cg_], gb = cb[cg_];
;                 const float v0 = cw[cv_], v1 = cw[NUP + cv_], v2 = cw[2 * NUP + cv_], vb = cb[cv_];
;                 float pg1 = 0.f, pg2 = 0.f, pv1 = 0.f, pv2 = 0.f;
; #pragma unroll
;                 for (int q = 0; q < 8; ++q) {
;                     float cgv = acc[q >> 2][0][q & 3][n][i], cvv = acc[q >> 2][1][q & 3][n][i];
;                     asm volatile("" : "+v"(cgv), "+v"(cvv) : "v"(chain));
;                     const float tg1 = dpp_ror<1>(cgv), tg2 = dpp_ror<2>(cgv), tv1 = dpp_ror<1>(cvv), tv2 = dpp_ror<2>(cvv);
;                     const float sg1 = fr >= 1 ? tg1 : pg1, sg2 = fr >= 2 ? tg2 : pg2, sv1 = fr >= 1 ? tv1 : pv1, sv2 = fr >= 2 ? tv2 : pv2;
;                     const float gg = gb + g0 * sg2 + g1 * sg1 + g2 * cgv;
;                     const float vv = vb + v0 * sv2 + v1 * sv1 + v2 * cvv;
;                     chain = gg * sigmoidf_(gg) * vv; acc[q >> 2][0][q & 3][n][i] = chain;
;                     pg1 = tg1; pg2 = tg2; pv1 = tv1; pv2 = tv2;
;                 }
	v_fma_f32 v80, v33, v36, v35
	v_pk_mul_f32 v[36:37], v[26:27], v[122:123]
	s_waitcnt vmcnt(2)
	v_fma_f32 v39, v32, v39, v34
	v_add_f32_e32 v37, v37, v80
	v_add_f32_e32 v100, v36, v37
	v_mul_f32_e32 v36, 0xbfb8aa3b, v100
	v_exp_f32_e32 v101, v36
	v_mov_b32_e32 v37, v26
	s_waitcnt vmcnt(0)
	v_pk_mul_f32 v[80:81], v[40:41], v[124:125]
	v_mov_b32_e32 v36, v40
	v_add_f32_e32 v26, 1.0, v101
	v_rcp_f32_e32 v40, v26
	v_add_f32_e32 v39, v81, v39
	v_add_f32_e32 v39, v80, v39
	v_mov_b32_e32 v26, v41
	v_mul_f32_e32 v40, v100, v40
	v_mul_f32_e32 v39, v39, v40
	v_mov_b32_dpp v87, v113 row_ror:2 row_mask:0xf bank_mask:0xf
	v_mov_b32_dpp v97, v112 row_ror:2 row_mask:0xf bank_mask:0xf
	v_mov_b32_dpp v86, v113 row_ror:1 row_mask:0xf bank_mask:0xf
	v_mov_b32_dpp v96, v112 row_ror:1 row_mask:0xf bank_mask:0xf
	v_cndmask_b32_e64 v81, v83, v87, s[40:41]
	v_cndmask_b32_e64 v80, v85, v97, s[40:41]
	v_cndmask_b32_e64 v41, v86, v67, s[38:39]
	v_cndmask_b32_e64 v40, v96, v84, s[38:39]
	v_pk_fma_f32 v[80:81], v[32:33], v[80:81], v[34:35]
	v_pk_fma_f32 v[40:41], v[26:27], v[40:41], v[80:81]
	s_nop 0
	v_pk_fma_f32 v[40:41], v[36:37], v[112:113], v[40:41]
	s_nop 0
	v_mul_f32_e32 v67, 0xbfb8aa3b, v41
	v_exp_f32_e32 v67, v67
	s_nop 0
	v_add_f32_e32 v67, 1.0, v67
	v_rcp_f32_e32 v67, v67
	s_nop 0
	v_mul_f32_e32 v41, v41, v67
	v_mul_f32_e32 v40, v40, v41
	v_mov_b32_dpp v100, v95 row_ror:2 row_mask:0xf bank_mask:0xf
	v_mov_b32_dpp v102, v94 row_ror:2 row_mask:0xf bank_mask:0xf
	v_mov_b32_dpp v83, v95 row_ror:1 row_mask:0xf bank_mask:0xf
	v_mov_b32_dpp v101, v94 row_ror:1 row_mask:0xf bank_mask:0xf
	v_cndmask_b32_e64 v85, v87, v100, s[40:41]
	v_cndmask_b32_e64 v84, v97, v102, s[40:41]
	v_cndmask_b32_e64 v81, v83, v86, s[38:39]
	v_cndmask_b32_e64 v80, v101, v96, s[38:39]
	v_pk_fma_f32 v[84:85], v[32:33], v[84:85], v[34:35]
	v_pk_fma_f32 v[80:81], v[26:27], v[80:81], v[84:85]
	v_pk_fma_f32 v[80:81], v[36:37], v[94:95], v[80:81]
	v_mul_f32_e32 v41, 0xbfb8aa3b, v81
	v_exp_f32_e32 v41, v41
	s_nop 0
	v_add_f32_e32 v41, 1.0, v41
	v_rcp_f32_e32 v41, v41
	s_nop 0
	v_mul_f32_e32 v41, v81, v41
	v_mul_f32_e32 v41, v80, v41
	v_mov_b32_dpp v87, v79 row_ror:2 row_mask:0xf bank_mask:0xf
	v_mov_b32_dpp v95, v78 row_ror:2 row_mask:0xf bank_mask:0xf
	v_mov_b32_dpp v86, v79 row_ror:1 row_mask:0xf bank_mask:0xf
	v_mov_b32_dpp v94, v78 row_ror:1 row_mask:0xf bank_mask:0xf
	v_cndmask_b32_e64 v85, v100, v87, s[40:41]
	v_cndmask_b32_e64 v84, v102, v95, s[40:41]
	v_cndmask_b32_e64 v81, v86, v83, s[38:39]
	v_cndmask_b32_e64 v80, v94, v101, s[38:39]
	v_pk_fma_f32 v[84:85], v[32:33], v[84:85], v[34:35]
	v_pk_fma_f32 v[80:81], v[26:27], v[80:81], v[84:85]
	v_pk_fma_f32 v[78:79], v[36:37], v[78:79], v[80:81]
	v_mul_f32_e32 v67, 0xbfb8aa3b, v79
	v_exp_f32_e32 v67, v67
	s_nop 0
	v_add_f32_e32 v67, 1.0, v67
	v_rcp_f32_e32 v67, v67
	s_nop 0
	v_mul_f32_e32 v67, v79, v67
	v_mul_f32_e32 v67, v78, v67
	v_mov_b32_dpp v84, v65 row_ror:2 row_mask:0xf bank_mask:0xf
	v_mov_b32_dpp v96, v64 row_ror:2 row_mask:0xf bank_mask:0xf
	v_mov_b32_dpp v83, v65 row_ror:1 row_mask:0xf bank_mask:0xf
	v_mov_b32_dpp v85, v64 row_ror:1 row_mask:0xf bank_mask:0xf
	v_cndmask_b32_e64 v81, v87, v84, s[40:41]
	v_cndmask_b32_e64 v80, v95, v96, s[40:41]
	v_cndmask_b32_e64 v79, v83, v86, s[38:39]
	v_cndmask_b32_e64 v78, v85, v94, s[38:39]
	v_pk_fma_f32 v[80:81], v[32:33], v[80:81], v[34:35]
	v_pk_fma_f32 v[78:79], v[26:27], v[78:79], v[80:81]
	v_pk_fma_f32 v[64:65], v[36:37], v[64:65], v[78:79]
	v_mul_f32_e32 v78, 0xbfb8aa3b, v65
	v_exp_f32_e32 v78, v78
	s_nop 0
	v_add_f32_e32 v78, 1.0, v78
	v_rcp_f32_e32 v78, v78
	s_nop 0
	v_mul_f32_e32 v65, v65, v78
	v_mul_f32_e32 v64, v64, v65
	v_mov_b32_dpp v87, v47 row_ror:2 row_mask:0xf bank_mask:0xf
	v_mov_b32_dpp v95, v46 row_ror:2 row_mask:0xf bank_mask:0xf
	v_mov_b32_dpp v86, v47 row_ror:1 row_mask:0xf bank_mask:0xf
	v_mov_b32_dpp v94, v46 row_ror:1 row_mask:0xf bank_mask:0xf
	v_cndmask_b32_e64 v81, v84, v87, s[40:41]
	v_cndmask_b32_e64 v80, v96, v95, s[40:41]
	v_cndmask_b32_e64 v79, v86, v83, s[38:39]
	v_cndmask_b32_e64 v78, v94, v85, s[38:39]
	v_pk_fma_f32 v[80:81], v[32:33], v[80:81], v[34:35]
	v_pk_fma_f32 v[78:79], v[26:27], v[78:79], v[80:81]
	v_pk_fma_f32 v[46:47], v[36:37], v[46:47], v[78:79]
	v_mul_f32_e32 v65, 0xbfb8aa3b, v47
	v_exp_f32_e32 v65, v65
	s_nop 0
	v_add_f32_e32 v65, 1.0, v65
	v_rcp_f32_e32 v65, v65
	s_nop 0
	v_mul_f32_e32 v47, v47, v65
	v_mul_f32_e32 v46, v46, v47
	v_mov_b32_dpp v84, v31 row_ror:2 row_mask:0xf bank_mask:0xf
	v_mov_b32_dpp v96, v30 row_ror:2 row_mask:0xf bank_mask:0xf
	v_mov_b32_dpp v83, v31 row_ror:1 row_mask:0xf bank_mask:0xf
	v_mov_b32_dpp v85, v30 row_ror:1 row_mask:0xf bank_mask:0xf
	v_cndmask_b32_e64 v81, v87, v84, s[40:41]
	v_cndmask_b32_e64 v80, v95, v96, s[40:41]
	v_cndmask_b32_e64 v79, v83, v86, s[38:39]
	v_cndmask_b32_e64 v78, v85, v94, s[38:39]
	v_pk_fma_f32 v[80:81], v[32:33], v[80:81], v[34:35]
	v_pk_fma_f32 v[78:79], v[26:27], v[78:79], v[80:81]
	v_pk_fma_f32 v[30:31], v[36:37], v[30:31], v[78:79]
	v_mul_f32_e32 v47, 0xbfb8aa3b, v31
	v_exp_f32_e32 v47, v47
	s_nop 0
	v_add_f32_e32 v47, 1.0, v47
	v_rcp_f32_e32 v47, v47
	s_nop 0
	v_mul_f32_e32 v31, v31, v47
	v_mul_f32_e32 v30, v30, v31
	v_mov_b32_dpp v80, v15 row_ror:2 row_mask:0xf bank_mask:0xf
	v_mov_b32_dpp v86, v14 row_ror:2 row_mask:0xf bank_mask:0xf
	v_mov_b32_dpp v65, v15 row_ror:1 row_mask:0xf bank_mask:0xf
	v_mov_b32_dpp v78, v14 row_ror:1 row_mask:0xf bank_mask:0xf
	v_cndmask_b32_e64 v81, v84, v80, s[40:41]
	v_cndmask_b32_e64 v80, v96, v86, s[40:41]
	v_cndmask_b32_e64 v79, v65, v83, s[38:39]
	v_cndmask_b32_e64 v78, v78, v85, s[38:39]
	v_pk_fma_f32 v[32:33], v[32:33], v[80:81], v[34:35]
	s_nop 0
	v_pk_fma_f32 v[26:27], v[26:27], v[78:79], v[32:33]
	s_nop 0
	v_pk_fma_f32 v[14:15], v[36:37], v[14:15], v[26:27]
	s_nop 0
	v_mul_f32_e32 v26, 0xbfb8aa3b, v15
	v_exp_f32_e32 v26, v26
	s_nop 0
	v_add_f32_e32 v26, 1.0, v26
	v_rcp_f32_e32 v26, v26
	s_nop 0
	v_mul_f32_e32 v15, v15, v26
	v_mul_f32_e32 v26, v14, v15
	global_load_dword v15, v[6:7], off offset:28
	s_nop 0
	global_load_dword v7, v[8:9], off offset:2076
	global_load_dword v6, v[10:11], off offset:28
	s_nop 0
	global_load_dword v9, v[16:17], off offset:28
	global_load_dword v14, v[18:19], off offset:3100
	s_nop 0
	global_load_dword v17, v[22:23], off offset:1052
	global_load_dword v16, v[24:25], off offset:3100
	global_load_dword v8, v[20:21], off offset:3100
	v_mov_b32_dpp v19, v120 row_ror:1 row_mask:0xf bank_mask:0xf
	v_mov_b32_dpp v22, v120 row_ror:2 row_mask:0xf bank_mask:0xf
	v_cndmask_b32_e64 v121, v19, 0, s[38:39]
	v_cndmask_b32_e64 v10, 0, v22, s[40:41]
	v_mov_b32_dpp v20, v110 row_ror:1 row_mask:0xf bank_mask:0xf
	v_mov_b32_dpp v24, v110 row_ror:2 row_mask:0xf bank_mask:0xf
	v_cndmask_b32_e64 v111, v20, 0, s[38:39]
	v_cndmask_b32_e64 v18, 0, v24, s[40:41]
	v_mov_b32_e32 v35, v3
	v_mov_b32_e32 v36, v3
	s_waitcnt vmcnt(4)
; __device__ __forceinline__ unsigned pk2(float lo, float hi) { const f32x2_t v = {lo, hi}; const bf16x2_t b = __builtin_convertvector(v, bf16x2_t); return __builtin_bit_cast(unsigned, b); }
; __device__ __forceinline__ float sigmoidf_(float x) { return __builtin_amdgcn_rcpf(1.0f + __expf(-x)); }
; template <int N> __device__ __forceinline__ float dpp_ror(float v) { return __builtin_bit_cast(float, __builtin_amdgcn_update_dpp(0, __builtin_bit_cast(int, v), 0x120 + N, 0xf, 0xf, false)); }
;     __device__ __forceinline__ void operator()(Acc& acc, const Unit& u, int wr, int wc, int fr, int fq) const {
;     ...
;             for (int i = 0; i < 4; ++i) {
;                 const int cg_ = ch0 + 4 * n + i, cv_ = DFF + cg_;
;                 const float g0 = cw[cg_], g1 = cw[NUP + cg_], g2 = cw[2 * NUP + cg_], gb = cb[cg_];
;                 const float v0 = cw[cv_], v1 = cw[NUP + cv_], v2 = cw[2 * NUP + cv_], vb = cb[cv_];
;                 float pg1 = 0.f, pg2 = 0.f, pv1 = 0.f, pv2 = 0.f;
; #pragma unroll
;                 for (int q = 0; q < 8; ++q) {
;                     float cgv = acc[q >> 2][0][q & 3][n][i], cvv = acc[q >> 2][1][q & 3][n][i];
;                     asm volatile("" : "+v"(cgv), "+v"(cvv) : "v"(chain));
;                     const float tg1 = dpp_ror<1>(cgv), tg2 = dpp_ror<2>(cgv), tv1 = dpp_ror<1>(cvv), tv2 = dpp_ror<2>(cvv);
;                     const float sg1 = fr >= 1 ? tg1 : pg1, sg2 = fr >= 2 ? tg2 : pg2, sv1 = fr >= 1 ? tv1 : pv1, sv2 = fr >= 2 ? tv2 : pv2;
;                     const float gg = gb + g0 * sg2 + g1 * sg1 + g2 * cgv;
;                     const float vv = vb + v0 * sv2 + v1 * sv1 + v2 * cvv;
;                     chain = gg * sigmoidf_(gg) * vv; acc[q >> 2][0][q & 3][n][i] = chain;
;                     pg1 = tg1; pg2 = tg2; pv1 = tv1; pv2 = tv2;
;                 }
;                 __builtin_amdgcn_sched_barrier(0);
;             }
;         }
; #pragma unroll
;         for (int q = 0; q < 8; ++q) {
;             const int t = tbase + 16 * q;
;             if ((16 * q + fr >= 2) && (t < SEQ)) {
;                 const f32x4 a0 = acc[q >> 2][0][q & 3][0], a1 = acc[q >> 2][0][q & 3][1];
;                 u32x4 w; w.x = pk2(a0[0], a0[1]); w.y = pk2(a0[2], a0[3]); w.z = pk2(a1[0], a1[1]); w.w = pk2(a1[2], a1[3]);
;                 *(u32x4*)(act + (size_t)(b * SEQ + t) * DFF + ch0) = w;
;             }
	v_fma_f32 v21, v15, v10, v9
	v_pk_mul_f32 v[10:11], v[6:7], v[120:121]
	s_waitcnt vmcnt(0)
	v_fma_f32 v18, v14, v18, v8
	v_add_f32_e32 v11, v11, v21
	v_add_f32_e32 v21, v10, v11
	v_pk_mul_f32 v[10:11], v[16:17], v[110:111]
	s_nop 0
	v_add_f32_e32 v11, v11, v18
	v_add_f32_e32 v10, v10, v11
	v_mul_f32_e32 v11, 0xbfb8aa3b, v21
	v_exp_f32_e32 v11, v11
	s_nop 0
	v_add_f32_e32 v11, 1.0, v11
	v_rcp_f32_e32 v11, v11
	s_nop 0
	v_mul_f32_e32 v11, v21, v11
	v_mul_f32_e32 v18, v10, v11
	v_mov_b32_e32 v11, v6
	v_mov_b32_e32 v6, v17
	v_mov_b32_dpp v27, v109 row_ror:2 row_mask:0xf bank_mask:0xf
	v_mov_b32_dpp v32, v108 row_ror:2 row_mask:0xf bank_mask:0xf
	v_mov_b32_dpp v25, v109 row_ror:1 row_mask:0xf bank_mask:0xf
	v_mov_b32_dpp v31, v108 row_ror:1 row_mask:0xf bank_mask:0xf
	v_cndmask_b32_e64 v23, v22, v27, s[40:41]
	v_cndmask_b32_e64 v22, v24, v32, s[40:41]
	v_cndmask_b32_e64 v21, v25, v19, s[38:39]
	v_cndmask_b32_e64 v20, v31, v20, s[38:39]
	v_pk_fma_f32 v[22:23], v[14:15], v[22:23], v[8:9]
	v_mov_b32_e32 v10, v16
	v_pk_fma_f32 v[16:17], v[6:7], v[20:21], v[22:23]
	v_pk_fma_f32 v[16:17], v[10:11], v[108:109], v[16:17]
	s_nop 0
	v_mul_f32_e32 v19, 0xbfb8aa3b, v17
	v_exp_f32_e32 v19, v19
	s_nop 0
	v_add_f32_e32 v19, 1.0, v19
	v_rcp_f32_e32 v19, v19
	s_nop 0
	v_mul_f32_e32 v17, v17, v19
	v_mul_f32_e32 v16, v16, v17
	v_mov_b32_dpp v24, v93 row_ror:2 row_mask:0xf bank_mask:0xf
	v_mov_b32_dpp v34, v92 row_ror:2 row_mask:0xf bank_mask:0xf
	v_mov_b32_dpp v19, v93 row_ror:1 row_mask:0xf bank_mask:0xf
	v_mov_b32_dpp v33, v92 row_ror:1 row_mask:0xf bank_mask:0xf
	v_cndmask_b32_e64 v23, v27, v24, s[40:41]
	v_cndmask_b32_e64 v22, v32, v34, s[40:41]
	v_cndmask_b32_e64 v21, v19, v25, s[38:39]
	v_cndmask_b32_e64 v20, v33, v31, s[38:39]
	v_pk_fma_f32 v[22:23], v[14:15], v[22:23], v[8:9]
	v_pk_fma_f32 v[20:21], v[6:7], v[20:21], v[22:23]
	v_pk_fma_f32 v[20:21], v[10:11], v[92:93], v[20:21]
	v_mul_f32_e32 v17, 0xbfb8aa3b, v21
	v_exp_f32_e32 v17, v17
	s_nop 0
	v_add_f32_e32 v17, 1.0, v17
	v_rcp_f32_e32 v17, v17
	s_nop 0
	v_mul_f32_e32 v17, v21, v17
	v_mul_f32_e32 v17, v20, v17
	v_mov_b32_dpp v27, v77 row_ror:2 row_mask:0xf bank_mask:0xf
	v_mov_b32_dpp v32, v76 row_ror:2 row_mask:0xf bank_mask:0xf
	v_mov_b32_dpp v25, v77 row_ror:1 row_mask:0xf bank_mask:0xf
	v_mov_b32_dpp v31, v76 row_ror:1 row_mask:0xf bank_mask:0xf
	v_cndmask_b32_e64 v23, v24, v27, s[40:41]
	v_cndmask_b32_e64 v22, v34, v32, s[40:41]
	v_cndmask_b32_e64 v21, v25, v19, s[38:39]
	v_cndmask_b32_e64 v20, v31, v33, s[38:39]
	v_pk_fma_f32 v[22:23], v[14:15], v[22:23], v[8:9]
	v_pk_fma_f32 v[20:21], v[6:7], v[20:21], v[22:23]
	v_pk_fma_f32 v[20:21], v[10:11], v[76:77], v[20:21]
	v_mul_f32_e32 v19, 0xbfb8aa3b, v21
	v_exp_f32_e32 v19, v19
	s_nop 0
	v_add_f32_e32 v19, 1.0, v19
	v_rcp_f32_e32 v19, v19
	s_nop 0
	v_mul_f32_e32 v19, v21, v19
	v_mul_f32_e32 v19, v20, v19
	v_mov_b32_dpp v33, v61 row_ror:2 row_mask:0xf bank_mask:0xf
	v_mov_b32_dpp v35, v60 row_ror:2 row_mask:0xf bank_mask:0xf
	v_mov_b32_dpp v24, v61 row_ror:1 row_mask:0xf bank_mask:0xf
	v_mov_b32_dpp v34, v60 row_ror:1 row_mask:0xf bank_mask:0xf
	v_cndmask_b32_e64 v23, v27, v33, s[40:41]
	v_cndmask_b32_e64 v22, v32, v35, s[40:41]
	v_cndmask_b32_e64 v21, v24, v25, s[38:39]
	v_cndmask_b32_e64 v20, v34, v31, s[38:39]
	v_pk_fma_f32 v[22:23], v[14:15], v[22:23], v[8:9]
	v_pk_fma_f32 v[20:21], v[6:7], v[20:21], v[22:23]
	v_pk_fma_f32 v[20:21], v[10:11], v[60:61], v[20:21]
	v_mul_f32_e32 v22, 0xbfb8aa3b, v21
	v_exp_f32_e32 v22, v22
	s_nop 0
	v_add_f32_e32 v22, 1.0, v22
	v_rcp_f32_e32 v22, v22
	s_nop 0
	v_mul_f32_e32 v21, v21, v22
	v_mul_f32_e32 v20, v20, v21
	v_mov_b32_dpp v27, v45 row_ror:1 row_mask:0xf bank_mask:0xf
	v_mov_b32_dpp v31, v45 row_ror:2 row_mask:0xf bank_mask:0xf
	v_mov_b32_dpp v36, v44 row_ror:2 row_mask:0xf bank_mask:0xf
	v_mov_b32_dpp v32, v44 row_ror:1 row_mask:0xf bank_mask:0xf
	v_cndmask_b32_e64 v23, v27, v24, s[38:39]
	v_cndmask_b32_e64 v25, v33, v31, s[40:41]
	v_cndmask_b32_e64 v24, v35, v36, s[40:41]
	v_cndmask_b32_e64 v22, v32, v34, s[38:39]
	v_pk_fma_f32 v[24:25], v[14:15], v[24:25], v[8:9]
	s_nop 0
	v_pk_fma_f32 v[22:23], v[6:7], v[22:23], v[24:25]
	v_pk_fma_f32 v[22:23], v[10:11], v[44:45], v[22:23]
	s_nop 0
	v_mul_f32_e32 v21, 0xbfb8aa3b, v23
	v_exp_f32_e32 v21, v21
	s_nop 0
	v_add_f32_e32 v21, 1.0, v21
	v_rcp_f32_e32 v21, v21
	s_nop 0
	v_mul_f32_e32 v21, v23, v21
	v_mul_f32_e32 v24, v22, v21
	v_mov_b32_dpp v22, v29 row_ror:2 row_mask:0xf bank_mask:0xf
	v_mov_b32_dpp v25, v28 row_ror:2 row_mask:0xf bank_mask:0xf
	v_mov_b32_dpp v21, v29 row_ror:1 row_mask:0xf bank_mask:0xf
	v_mov_b32_dpp v23, v28 row_ror:1 row_mask:0xf bank_mask:0xf
	v_cndmask_b32_e64 v35, v31, v22, s[40:41]
	v_cndmask_b32_e64 v34, v36, v25, s[40:41]
	v_cndmask_b32_e64 v33, v21, v27, s[38:39]
	v_cndmask_b32_e64 v32, v23, v32, s[38:39]
	v_pk_fma_f32 v[34:35], v[14:15], v[34:35], v[8:9]
	v_pk_fma_f32 v[32:33], v[6:7], v[32:33], v[34:35]
	s_nop 0
	v_pk_fma_f32 v[28:29], v[10:11], v[28:29], v[32:33]
	v_mul_f32_e32 v27, 0xbfb8aa3b, v29
	v_exp_f32_e32 v27, v27
	s_nop 0
	v_add_f32_e32 v27, 1.0, v27
	v_rcp_f32_e32 v27, v27
	s_nop 0
	v_mul_f32_e32 v27, v29, v27
	v_mul_f32_e32 v27, v28, v27
	s_nop 0
	v_mov_b32_dpp v28, v13 row_ror:1 row_mask:0xf bank_mask:0xf
	v_mov_b32_dpp v29, v13 row_ror:2 row_mask:0xf bank_mask:0xf
	v_mov_b32_dpp v31, v12 row_ror:1 row_mask:0xf bank_mask:0xf
	v_mov_b32_dpp v32, v12 row_ror:2 row_mask:0xf bank_mask:0xf
	v_cmp_gt_i32_e32 vcc, s97, v198
	s_and_b64 s[44:45], s[40:41], vcc
	s_and_saveexec_b64 s[34:35], s[44:45]
	s_cbranch_execz .LBB0_45
	v_cvt_pk_bf16_f32 v37, v39, v18
	v_add_u32_e32 v18, s20, v198
	v_mov_b64_e32 v[44:45], s[8:9]
	s_movk_i32 s21, 0x1600
	v_mad_i64_i32 v[44:45], s[44:45], v18, s21, v[44:45]
	v_cvt_pk_bf16_f32 v34, v184, v137
	v_cvt_pk_bf16_f32 v35, v99, v63
	v_cvt_pk_bf16_f32 v36, v56, v43
	v_lshl_add_u64 v[44:45], v[4:5], 1, v[44:45]
	flat_store_dwordx4 v[44:45], v[34:37]
